# P6: f32 accumulators carried from the four-branch GEMM into the memory-branch GEMM (all five branches merged in registers, single bf16 rounding at y; no running-sum round trip at all)
# speedup vs baseline: 1.0103x; 1.0058x over previous
.LBB0_1757:
	s_load_dwordx2 s[2:3], s[62:63], 0xc0
	v_lshrrev_b32_e32 v164, 8, v208
	v_and_b32_e32 v165, 15, v208
	v_lshl_add_u32 v164, v164, 6, v165
	v_bfe_u32 v165, v208, 6, 2
	v_bfe_u32 v166, v208, 4, 2
	v_lshlrev_b32_e32 v165, 6, v165
	v_lshl_add_u32 v165, v166, 4, v165
	v_lshl_add_u32 v216, v164, 9, v165
	v_lshl_add_u32 v221, v164, 11, v165
	s_mul_i32 s0, s48, 49
	s_lshl_b32 s19, s46, 2
	s_add_i32 s0, s0, s19
	s_add_i32 s0, s0, s47
	s_add_i32 s0, s0, 29
	s_lshl_b32 s0, s0, 17
	s_lshl_b32 s19, s48, 19
	s_lshl_b32 s32, s47, 9
	s_add_i32 s19, s19, s32
	s_mov_b32 s60, 0xbfb8aa3b
	s_mov_b32 s61, 0xbfb8aa3b
	s_mov_b32 s78, 1.0
	s_mov_b32 s79, 1.0
	s_waitcnt lgkmcnt(0)
	s_add_u32 s24, s2, 0x74c2800
	s_addc_u32 s25, s3, 0
	s_add_u32 s24, s24, s0
	s_addc_u32 s25, s25, 0
	s_add_u32 s26, s2, 0x244c2800
	s_addc_u32 s27, s3, 0
	s_add_u32 s26, s26, s19
	s_addc_u32 s27, s27, 0
	s_add_u32 s8, s24, 0x0
	s_addc_u32 s9, s25, 0
	global_load_dwordx4 v[132:135], v216, s[8:9]
	s_add_u32 s8, s24, 0x80000
	s_addc_u32 s9, s25, 0
	global_load_dwordx4 v[148:151], v216, s[8:9]
	s_add_u32 s8, s24, 0x0
	s_addc_u32 s9, s25, 0
	global_load_dwordx4 v[136:139], v216, s[8:9] offset:256
	s_add_u32 s8, s24, 0x80000
	s_addc_u32 s9, s25, 0
	global_load_dwordx4 v[152:155], v216, s[8:9] offset:256
	s_add_u32 s8, s24, 0x2000
	s_addc_u32 s9, s25, 0
	global_load_dwordx4 v[140:143], v216, s[8:9]
	s_add_u32 s8, s24, 0x82000
	s_addc_u32 s9, s25, 0
	global_load_dwordx4 v[156:159], v216, s[8:9]
	s_add_u32 s8, s24, 0x2000
	s_addc_u32 s9, s25, 0
	global_load_dwordx4 v[144:147], v216, s[8:9] offset:256
	s_add_u32 s8, s24, 0x82000
	s_addc_u32 s9, s25, 0
	global_load_dwordx4 v[160:163], v216, s[8:9] offset:256
	s_add_u32 s8, s24, 0x4000
	s_addc_u32 s9, s25, 0
	global_load_dwordx4 v[224:227], v216, s[8:9]
	s_add_u32 s8, s24, 0x84000
	s_addc_u32 s9, s25, 0
	global_load_dwordx4 v[194:197], v216, s[8:9]
	s_add_u32 s8, s24, 0x4000
	s_addc_u32 s9, s25, 0
	global_load_dwordx4 v[228:231], v216, s[8:9] offset:256
	s_add_u32 s8, s24, 0x84000
	s_addc_u32 s9, s25, 0
	global_load_dwordx4 v[198:201], v216, s[8:9] offset:256
	s_add_u32 s8, s24, 0x6000
	s_addc_u32 s9, s25, 0
	global_load_dwordx4 v[232:235], v216, s[8:9]
	s_add_u32 s8, s24, 0x86000
	s_addc_u32 s9, s25, 0
	global_load_dwordx4 v[202:205], v216, s[8:9]
	s_add_u32 s8, s24, 0x6000
	s_addc_u32 s9, s25, 0
	global_load_dwordx4 v[236:239], v216, s[8:9] offset:256
	s_add_u32 s8, s24, 0x86000
	s_addc_u32 s9, s25, 0
	global_load_dwordx4 v[240:243], v216, s[8:9] offset:256
	s_waitcnt vmcnt(14)
	s_add_u32 s98, s26, 0x0
	s_addc_u32 s99, s27, 0
	v_lshlrev_b32_e32 v164, 16, v132
	v_lshlrev_b32_e32 v170, 16, v133
	v_lshlrev_b32_e32 v172, 16, v134
	v_lshlrev_b32_e32 v206, 16, v135
	v_and_b32_e32 v165, 0xffff0000, v132
	v_and_b32_e32 v171, 0xffff0000, v133
	v_and_b32_e32 v173, 0xffff0000, v134
	v_and_b32_e32 v207, 0xffff0000, v135
	v_lshlrev_b32_e32 v210, 16, v148
	v_lshlrev_b32_e32 v244, 16, v149
	v_lshlrev_b32_e32 v248, 16, v150
	v_lshlrev_b32_e32 v250, 16, v151
	v_and_b32_e32 v211, 0xffff0000, v148
	v_and_b32_e32 v245, 0xffff0000, v149
	v_and_b32_e32 v249, 0xffff0000, v150
	v_and_b32_e32 v251, 0xffff0000, v151
	v_pk_mul_f32 v[164:165], v[164:165], s[60:61]
	v_pk_mul_f32 v[170:171], v[170:171], s[60:61]
	v_pk_mul_f32 v[172:173], v[172:173], s[60:61]
	v_pk_mul_f32 v[206:207], v[206:207], s[60:61]
	v_pk_mul_f32 v[210:211], v[210:211], s[60:61]
	v_pk_mul_f32 v[244:245], v[244:245], s[60:61]
	v_pk_mul_f32 v[248:249], v[248:249], s[60:61]
	v_pk_mul_f32 v[250:251], v[250:251], s[60:61]
	v_exp_f32_e32 v164, v164
	v_exp_f32_e32 v170, v170
	v_exp_f32_e32 v172, v172
	v_exp_f32_e32 v206, v206
	v_exp_f32_e32 v165, v165
	v_exp_f32_e32 v171, v171
	v_exp_f32_e32 v173, v173
	v_exp_f32_e32 v207, v207
	v_exp_f32_e32 v210, v210
	v_exp_f32_e32 v244, v244
	v_exp_f32_e32 v248, v248
	v_exp_f32_e32 v250, v250
	v_exp_f32_e32 v211, v211
	v_exp_f32_e32 v245, v245
	v_exp_f32_e32 v249, v249
	v_exp_f32_e32 v251, v251
	v_pk_add_f32 v[164:165], v[164:165], s[78:79]
	v_pk_add_f32 v[170:171], v[170:171], s[78:79]
	v_pk_add_f32 v[172:173], v[172:173], s[78:79]
	v_pk_add_f32 v[206:207], v[206:207], s[78:79]
	v_pk_add_f32 v[210:211], v[210:211], s[78:79]
	v_pk_add_f32 v[244:245], v[244:245], s[78:79]
	v_pk_add_f32 v[248:249], v[248:249], s[78:79]
	v_pk_add_f32 v[250:251], v[250:251], s[78:79]
	v_rcp_f32_e32 v164, v164
	v_rcp_f32_e32 v170, v170
	v_rcp_f32_e32 v172, v172
	v_rcp_f32_e32 v206, v206
	v_rcp_f32_e32 v165, v165
	v_rcp_f32_e32 v171, v171
	v_rcp_f32_e32 v173, v173
	v_rcp_f32_e32 v207, v207
	s_nop 0
	v_pk_mul_f32 v[164:165], v[164:165], v[210:211]
	v_pk_mul_f32 v[170:171], v[170:171], v[244:245]
	v_pk_mul_f32 v[172:173], v[172:173], v[248:249]
	v_pk_mul_f32 v[206:207], v[206:207], v[250:251]
	v_pk_mul_f32 v[128:129], v[128:129], v[164:165]
	v_pk_mul_f32 v[130:131], v[130:131], v[170:171]
	v_pk_mul_f32 v[124:125], v[124:125], v[172:173]
	v_pk_mul_f32 v[126:127], v[126:127], v[206:207]
	s_add_u32 s8, s24, 0x10000
	s_addc_u32 s9, s25, 0
	global_load_dwordx4 v[132:135], v216, s[8:9]
	s_add_u32 s8, s24, 0x90000
	s_addc_u32 s9, s25, 0
	global_load_dwordx4 v[148:151], v216, s[8:9]
	s_waitcnt vmcnt(14)
	s_add_u32 s98, s26, 0x0
	s_addc_u32 s99, s27, 0
	v_lshlrev_b32_e32 v164, 16, v136
	v_lshlrev_b32_e32 v170, 16, v137
	v_lshlrev_b32_e32 v172, 16, v138
	v_lshlrev_b32_e32 v206, 16, v139
	v_and_b32_e32 v165, 0xffff0000, v136
	v_and_b32_e32 v171, 0xffff0000, v137
	v_and_b32_e32 v173, 0xffff0000, v138
	v_and_b32_e32 v207, 0xffff0000, v139
	v_lshlrev_b32_e32 v210, 16, v152
	v_lshlrev_b32_e32 v244, 16, v153
	v_lshlrev_b32_e32 v248, 16, v154
	v_lshlrev_b32_e32 v250, 16, v155
	v_and_b32_e32 v211, 0xffff0000, v152
	v_and_b32_e32 v245, 0xffff0000, v153
	v_and_b32_e32 v249, 0xffff0000, v154
	v_and_b32_e32 v251, 0xffff0000, v155
	v_pk_mul_f32 v[164:165], v[164:165], s[60:61]
	v_pk_mul_f32 v[170:171], v[170:171], s[60:61]
	v_pk_mul_f32 v[172:173], v[172:173], s[60:61]
	v_pk_mul_f32 v[206:207], v[206:207], s[60:61]
	v_pk_mul_f32 v[210:211], v[210:211], s[60:61]
	v_pk_mul_f32 v[244:245], v[244:245], s[60:61]
	v_pk_mul_f32 v[248:249], v[248:249], s[60:61]
	v_pk_mul_f32 v[250:251], v[250:251], s[60:61]
	v_exp_f32_e32 v164, v164
	v_exp_f32_e32 v170, v170
	v_exp_f32_e32 v172, v172
	v_exp_f32_e32 v206, v206
	v_exp_f32_e32 v165, v165
	v_exp_f32_e32 v171, v171
	v_exp_f32_e32 v173, v173
	v_exp_f32_e32 v207, v207
	v_exp_f32_e32 v210, v210
	v_exp_f32_e32 v244, v244
	v_exp_f32_e32 v248, v248
	v_exp_f32_e32 v250, v250
	v_exp_f32_e32 v211, v211
	v_exp_f32_e32 v245, v245
	v_exp_f32_e32 v249, v249
	v_exp_f32_e32 v251, v251
	v_pk_add_f32 v[164:165], v[164:165], s[78:79]
	v_pk_add_f32 v[170:171], v[170:171], s[78:79]
	v_pk_add_f32 v[172:173], v[172:173], s[78:79]
	v_pk_add_f32 v[206:207], v[206:207], s[78:79]
	v_pk_add_f32 v[210:211], v[210:211], s[78:79]
	v_pk_add_f32 v[244:245], v[244:245], s[78:79]
	v_pk_add_f32 v[248:249], v[248:249], s[78:79]
	v_pk_add_f32 v[250:251], v[250:251], s[78:79]
	v_rcp_f32_e32 v164, v164
	v_rcp_f32_e32 v170, v170
	v_rcp_f32_e32 v172, v172
	v_rcp_f32_e32 v206, v206
	v_rcp_f32_e32 v165, v165
	v_rcp_f32_e32 v171, v171
	v_rcp_f32_e32 v173, v173
	v_rcp_f32_e32 v207, v207
	s_nop 0
	v_pk_mul_f32 v[164:165], v[164:165], v[210:211]
	v_pk_mul_f32 v[170:171], v[170:171], v[244:245]
	v_pk_mul_f32 v[172:173], v[172:173], v[248:249]
	v_pk_mul_f32 v[206:207], v[206:207], v[250:251]
	v_pk_mul_f32 v[120:121], v[120:121], v[164:165]
	v_pk_mul_f32 v[122:123], v[122:123], v[170:171]
	v_pk_mul_f32 v[116:117], v[116:117], v[172:173]
	v_pk_mul_f32 v[118:119], v[118:119], v[206:207]
	s_add_u32 s8, s24, 0x10000
	s_addc_u32 s9, s25, 0
	global_load_dwordx4 v[136:139], v216, s[8:9] offset:256
	s_add_u32 s8, s24, 0x90000
	s_addc_u32 s9, s25, 0
	global_load_dwordx4 v[152:155], v216, s[8:9] offset:256
	s_waitcnt vmcnt(14)
	s_add_u32 s98, s26, 0x8000
	s_addc_u32 s99, s27, 0
	v_lshlrev_b32_e32 v164, 16, v140
	v_lshlrev_b32_e32 v170, 16, v141
	v_lshlrev_b32_e32 v172, 16, v142
	v_lshlrev_b32_e32 v206, 16, v143
	v_and_b32_e32 v165, 0xffff0000, v140
	v_and_b32_e32 v171, 0xffff0000, v141
	v_and_b32_e32 v173, 0xffff0000, v142
	v_and_b32_e32 v207, 0xffff0000, v143
	v_lshlrev_b32_e32 v210, 16, v156
	v_lshlrev_b32_e32 v244, 16, v157
	v_lshlrev_b32_e32 v248, 16, v158
	v_lshlrev_b32_e32 v250, 16, v159
	v_and_b32_e32 v211, 0xffff0000, v156
	v_and_b32_e32 v245, 0xffff0000, v157
	v_and_b32_e32 v249, 0xffff0000, v158
	v_and_b32_e32 v251, 0xffff0000, v159
	v_pk_mul_f32 v[164:165], v[164:165], s[60:61]
	v_pk_mul_f32 v[170:171], v[170:171], s[60:61]
	v_pk_mul_f32 v[172:173], v[172:173], s[60:61]
	v_pk_mul_f32 v[206:207], v[206:207], s[60:61]
	v_pk_mul_f32 v[210:211], v[210:211], s[60:61]
	v_pk_mul_f32 v[244:245], v[244:245], s[60:61]
	v_pk_mul_f32 v[248:249], v[248:249], s[60:61]
	v_pk_mul_f32 v[250:251], v[250:251], s[60:61]
	v_exp_f32_e32 v164, v164
	v_exp_f32_e32 v170, v170
	v_exp_f32_e32 v172, v172
	v_exp_f32_e32 v206, v206
	v_exp_f32_e32 v165, v165
	v_exp_f32_e32 v171, v171
	v_exp_f32_e32 v173, v173
	v_exp_f32_e32 v207, v207
	v_exp_f32_e32 v210, v210
	v_exp_f32_e32 v244, v244
	v_exp_f32_e32 v248, v248
	v_exp_f32_e32 v250, v250
	v_exp_f32_e32 v211, v211
	v_exp_f32_e32 v245, v245
	v_exp_f32_e32 v249, v249
	v_exp_f32_e32 v251, v251
	v_pk_add_f32 v[164:165], v[164:165], s[78:79]
	v_pk_add_f32 v[170:171], v[170:171], s[78:79]
	v_pk_add_f32 v[172:173], v[172:173], s[78:79]
	v_pk_add_f32 v[206:207], v[206:207], s[78:79]
	v_pk_add_f32 v[210:211], v[210:211], s[78:79]
	v_pk_add_f32 v[244:245], v[244:245], s[78:79]
	v_pk_add_f32 v[248:249], v[248:249], s[78:79]
	v_pk_add_f32 v[250:251], v[250:251], s[78:79]
	v_rcp_f32_e32 v164, v164
	v_rcp_f32_e32 v170, v170
	v_rcp_f32_e32 v172, v172
	v_rcp_f32_e32 v206, v206
	v_rcp_f32_e32 v165, v165
	v_rcp_f32_e32 v171, v171
	v_rcp_f32_e32 v173, v173
	v_rcp_f32_e32 v207, v207
	s_nop 0
	v_pk_mul_f32 v[164:165], v[164:165], v[210:211]
	v_pk_mul_f32 v[170:171], v[170:171], v[244:245]
	v_pk_mul_f32 v[172:173], v[172:173], v[248:249]
	v_pk_mul_f32 v[206:207], v[206:207], v[250:251]
	v_pk_mul_f32 v[112:113], v[112:113], v[164:165]
	v_pk_mul_f32 v[114:115], v[114:115], v[170:171]
	v_pk_mul_f32 v[108:109], v[108:109], v[172:173]
	v_pk_mul_f32 v[110:111], v[110:111], v[206:207]
	s_add_u32 s8, s24, 0x12000
	s_addc_u32 s9, s25, 0
	global_load_dwordx4 v[140:143], v216, s[8:9]
	s_add_u32 s8, s24, 0x92000
	s_addc_u32 s9, s25, 0
	global_load_dwordx4 v[156:159], v216, s[8:9]
	s_waitcnt vmcnt(14)
	s_add_u32 s98, s26, 0x8000
	s_addc_u32 s99, s27, 0
	v_lshlrev_b32_e32 v164, 16, v144
	v_lshlrev_b32_e32 v170, 16, v145
	v_lshlrev_b32_e32 v172, 16, v146
	v_lshlrev_b32_e32 v206, 16, v147
	v_and_b32_e32 v165, 0xffff0000, v144
	v_and_b32_e32 v171, 0xffff0000, v145
	v_and_b32_e32 v173, 0xffff0000, v146
	v_and_b32_e32 v207, 0xffff0000, v147
	v_lshlrev_b32_e32 v210, 16, v160
	v_lshlrev_b32_e32 v244, 16, v161
	v_lshlrev_b32_e32 v248, 16, v162
	v_lshlrev_b32_e32 v250, 16, v163
	v_and_b32_e32 v211, 0xffff0000, v160
	v_and_b32_e32 v245, 0xffff0000, v161
	v_and_b32_e32 v249, 0xffff0000, v162
	v_and_b32_e32 v251, 0xffff0000, v163
	v_pk_mul_f32 v[164:165], v[164:165], s[60:61]
	v_pk_mul_f32 v[170:171], v[170:171], s[60:61]
	v_pk_mul_f32 v[172:173], v[172:173], s[60:61]
	v_pk_mul_f32 v[206:207], v[206:207], s[60:61]
	v_pk_mul_f32 v[210:211], v[210:211], s[60:61]
	v_pk_mul_f32 v[244:245], v[244:245], s[60:61]
	v_pk_mul_f32 v[248:249], v[248:249], s[60:61]
	v_pk_mul_f32 v[250:251], v[250:251], s[60:61]
	v_exp_f32_e32 v164, v164
	v_exp_f32_e32 v170, v170
	v_exp_f32_e32 v172, v172
	v_exp_f32_e32 v206, v206
	v_exp_f32_e32 v165, v165
	v_exp_f32_e32 v171, v171
	v_exp_f32_e32 v173, v173
	v_exp_f32_e32 v207, v207
	v_exp_f32_e32 v210, v210
	v_exp_f32_e32 v244, v244
	v_exp_f32_e32 v248, v248
	v_exp_f32_e32 v250, v250
	v_exp_f32_e32 v211, v211
	v_exp_f32_e32 v245, v245
	v_exp_f32_e32 v249, v249
	v_exp_f32_e32 v251, v251
	v_pk_add_f32 v[164:165], v[164:165], s[78:79]
	v_pk_add_f32 v[170:171], v[170:171], s[78:79]
	v_pk_add_f32 v[172:173], v[172:173], s[78:79]
	v_pk_add_f32 v[206:207], v[206:207], s[78:79]
	v_pk_add_f32 v[210:211], v[210:211], s[78:79]
	v_pk_add_f32 v[244:245], v[244:245], s[78:79]
	v_pk_add_f32 v[248:249], v[248:249], s[78:79]
	v_pk_add_f32 v[250:251], v[250:251], s[78:79]
	v_rcp_f32_e32 v164, v164
	v_rcp_f32_e32 v170, v170
	v_rcp_f32_e32 v172, v172
	v_rcp_f32_e32 v206, v206
	v_rcp_f32_e32 v165, v165
	v_rcp_f32_e32 v171, v171
	v_rcp_f32_e32 v173, v173
	v_rcp_f32_e32 v207, v207
	s_nop 0
	v_pk_mul_f32 v[164:165], v[164:165], v[210:211]
	v_pk_mul_f32 v[170:171], v[170:171], v[244:245]
	v_pk_mul_f32 v[172:173], v[172:173], v[248:249]
	v_pk_mul_f32 v[206:207], v[206:207], v[250:251]
	v_pk_mul_f32 v[104:105], v[104:105], v[164:165]
	v_pk_mul_f32 v[106:107], v[106:107], v[170:171]
	v_pk_mul_f32 v[100:101], v[100:101], v[172:173]
	v_pk_mul_f32 v[102:103], v[102:103], v[206:207]
	s_add_u32 s8, s24, 0x12000
	s_addc_u32 s9, s25, 0
	global_load_dwordx4 v[144:147], v216, s[8:9] offset:256
	s_add_u32 s8, s24, 0x92000
	s_addc_u32 s9, s25, 0
	global_load_dwordx4 v[160:163], v216, s[8:9] offset:256
	s_waitcnt vmcnt(14)
	s_add_u32 s98, s26, 0x10000
	s_addc_u32 s99, s27, 0
	v_lshlrev_b32_e32 v164, 16, v224
	v_lshlrev_b32_e32 v170, 16, v225
	v_lshlrev_b32_e32 v172, 16, v226
	v_lshlrev_b32_e32 v206, 16, v227
	v_and_b32_e32 v165, 0xffff0000, v224
	v_and_b32_e32 v171, 0xffff0000, v225
	v_and_b32_e32 v173, 0xffff0000, v226
	v_and_b32_e32 v207, 0xffff0000, v227
	v_lshlrev_b32_e32 v210, 16, v194
	v_lshlrev_b32_e32 v244, 16, v195
	v_lshlrev_b32_e32 v248, 16, v196
	v_lshlrev_b32_e32 v250, 16, v197
	v_and_b32_e32 v211, 0xffff0000, v194
	v_and_b32_e32 v245, 0xffff0000, v195
	v_and_b32_e32 v249, 0xffff0000, v196
	v_and_b32_e32 v251, 0xffff0000, v197
	v_pk_mul_f32 v[164:165], v[164:165], s[60:61]
	v_pk_mul_f32 v[170:171], v[170:171], s[60:61]
	v_pk_mul_f32 v[172:173], v[172:173], s[60:61]
	v_pk_mul_f32 v[206:207], v[206:207], s[60:61]
	v_pk_mul_f32 v[210:211], v[210:211], s[60:61]
	v_pk_mul_f32 v[244:245], v[244:245], s[60:61]
	v_pk_mul_f32 v[248:249], v[248:249], s[60:61]
	v_pk_mul_f32 v[250:251], v[250:251], s[60:61]
	v_exp_f32_e32 v164, v164
	v_exp_f32_e32 v170, v170
	v_exp_f32_e32 v172, v172
	v_exp_f32_e32 v206, v206
	v_exp_f32_e32 v165, v165
	v_exp_f32_e32 v171, v171
	v_exp_f32_e32 v173, v173
	v_exp_f32_e32 v207, v207
	v_exp_f32_e32 v210, v210
	v_exp_f32_e32 v244, v244
	v_exp_f32_e32 v248, v248
	v_exp_f32_e32 v250, v250
	v_exp_f32_e32 v211, v211
	v_exp_f32_e32 v245, v245
	v_exp_f32_e32 v249, v249
	v_exp_f32_e32 v251, v251
	v_pk_add_f32 v[164:165], v[164:165], s[78:79]
	v_pk_add_f32 v[170:171], v[170:171], s[78:79]
	v_pk_add_f32 v[172:173], v[172:173], s[78:79]
	v_pk_add_f32 v[206:207], v[206:207], s[78:79]
	v_pk_add_f32 v[210:211], v[210:211], s[78:79]
	v_pk_add_f32 v[244:245], v[244:245], s[78:79]
	v_pk_add_f32 v[248:249], v[248:249], s[78:79]
	v_pk_add_f32 v[250:251], v[250:251], s[78:79]
	v_rcp_f32_e32 v164, v164
	v_rcp_f32_e32 v170, v170
	v_rcp_f32_e32 v172, v172
	v_rcp_f32_e32 v206, v206
	v_rcp_f32_e32 v165, v165
	v_rcp_f32_e32 v171, v171
	v_rcp_f32_e32 v173, v173
	v_rcp_f32_e32 v207, v207
	s_nop 0
	v_pk_mul_f32 v[164:165], v[164:165], v[210:211]
	v_pk_mul_f32 v[170:171], v[170:171], v[244:245]
	v_pk_mul_f32 v[172:173], v[172:173], v[248:249]
	v_pk_mul_f32 v[206:207], v[206:207], v[250:251]
	v_pk_mul_f32 v[96:97], v[96:97], v[164:165]
	v_pk_mul_f32 v[98:99], v[98:99], v[170:171]
	v_pk_mul_f32 v[92:93], v[92:93], v[172:173]
	v_pk_mul_f32 v[94:95], v[94:95], v[206:207]
	s_add_u32 s8, s24, 0x14000
	s_addc_u32 s9, s25, 0
	global_load_dwordx4 v[224:227], v216, s[8:9]
	s_add_u32 s8, s24, 0x94000
	s_addc_u32 s9, s25, 0
	global_load_dwordx4 v[194:197], v216, s[8:9]
	s_waitcnt vmcnt(14)
	s_add_u32 s98, s26, 0x10000
	s_addc_u32 s99, s27, 0
	v_lshlrev_b32_e32 v164, 16, v228
	v_lshlrev_b32_e32 v170, 16, v229
	v_lshlrev_b32_e32 v172, 16, v230
	v_lshlrev_b32_e32 v206, 16, v231
	v_and_b32_e32 v165, 0xffff0000, v228
	v_and_b32_e32 v171, 0xffff0000, v229
	v_and_b32_e32 v173, 0xffff0000, v230
	v_and_b32_e32 v207, 0xffff0000, v231
	v_lshlrev_b32_e32 v210, 16, v198
	v_lshlrev_b32_e32 v244, 16, v199
	v_lshlrev_b32_e32 v248, 16, v200
	v_lshlrev_b32_e32 v250, 16, v201
	v_and_b32_e32 v211, 0xffff0000, v198
	v_and_b32_e32 v245, 0xffff0000, v199
	v_and_b32_e32 v249, 0xffff0000, v200
	v_and_b32_e32 v251, 0xffff0000, v201
	v_pk_mul_f32 v[164:165], v[164:165], s[60:61]
	v_pk_mul_f32 v[170:171], v[170:171], s[60:61]
	v_pk_mul_f32 v[172:173], v[172:173], s[60:61]
	v_pk_mul_f32 v[206:207], v[206:207], s[60:61]
	v_pk_mul_f32 v[210:211], v[210:211], s[60:61]
	v_pk_mul_f32 v[244:245], v[244:245], s[60:61]
	v_pk_mul_f32 v[248:249], v[248:249], s[60:61]
	v_pk_mul_f32 v[250:251], v[250:251], s[60:61]
	v_exp_f32_e32 v164, v164
	v_exp_f32_e32 v170, v170
	v_exp_f32_e32 v172, v172
	v_exp_f32_e32 v206, v206
	v_exp_f32_e32 v165, v165
	v_exp_f32_e32 v171, v171
	v_exp_f32_e32 v173, v173
	v_exp_f32_e32 v207, v207
	v_exp_f32_e32 v210, v210
	v_exp_f32_e32 v244, v244
	v_exp_f32_e32 v248, v248
	v_exp_f32_e32 v250, v250
	v_exp_f32_e32 v211, v211
	v_exp_f32_e32 v245, v245
	v_exp_f32_e32 v249, v249
	v_exp_f32_e32 v251, v251
	v_pk_add_f32 v[164:165], v[164:165], s[78:79]
	v_pk_add_f32 v[170:171], v[170:171], s[78:79]
	v_pk_add_f32 v[172:173], v[172:173], s[78:79]
	v_pk_add_f32 v[206:207], v[206:207], s[78:79]
	v_pk_add_f32 v[210:211], v[210:211], s[78:79]
	v_pk_add_f32 v[244:245], v[244:245], s[78:79]
	v_pk_add_f32 v[248:249], v[248:249], s[78:79]
	v_pk_add_f32 v[250:251], v[250:251], s[78:79]
	v_rcp_f32_e32 v164, v164
	v_rcp_f32_e32 v170, v170
	v_rcp_f32_e32 v172, v172
	v_rcp_f32_e32 v206, v206
	v_rcp_f32_e32 v165, v165
	v_rcp_f32_e32 v171, v171
	v_rcp_f32_e32 v173, v173
	v_rcp_f32_e32 v207, v207
	s_nop 0
	v_pk_mul_f32 v[164:165], v[164:165], v[210:211]
	v_pk_mul_f32 v[170:171], v[170:171], v[244:245]
	v_pk_mul_f32 v[172:173], v[172:173], v[248:249]
	v_pk_mul_f32 v[206:207], v[206:207], v[250:251]
	v_pk_mul_f32 v[88:89], v[88:89], v[164:165]
	v_pk_mul_f32 v[90:91], v[90:91], v[170:171]
	v_pk_mul_f32 v[84:85], v[84:85], v[172:173]
	v_pk_mul_f32 v[86:87], v[86:87], v[206:207]
	s_add_u32 s8, s24, 0x14000
	s_addc_u32 s9, s25, 0
	global_load_dwordx4 v[228:231], v216, s[8:9] offset:256
	s_add_u32 s8, s24, 0x94000
	s_addc_u32 s9, s25, 0
	global_load_dwordx4 v[198:201], v216, s[8:9] offset:256
	s_waitcnt vmcnt(14)
	s_add_u32 s98, s26, 0x18000
	s_addc_u32 s99, s27, 0
	v_lshlrev_b32_e32 v164, 16, v232
	v_lshlrev_b32_e32 v170, 16, v233
	v_lshlrev_b32_e32 v172, 16, v234
	v_lshlrev_b32_e32 v206, 16, v235
	v_and_b32_e32 v165, 0xffff0000, v232
	v_and_b32_e32 v171, 0xffff0000, v233
	v_and_b32_e32 v173, 0xffff0000, v234
	v_and_b32_e32 v207, 0xffff0000, v235
	v_lshlrev_b32_e32 v210, 16, v202
	v_lshlrev_b32_e32 v244, 16, v203
	v_lshlrev_b32_e32 v248, 16, v204
	v_lshlrev_b32_e32 v250, 16, v205
	v_and_b32_e32 v211, 0xffff0000, v202
	v_and_b32_e32 v245, 0xffff0000, v203
	v_and_b32_e32 v249, 0xffff0000, v204
	v_and_b32_e32 v251, 0xffff0000, v205
	v_pk_mul_f32 v[164:165], v[164:165], s[60:61]
	v_pk_mul_f32 v[170:171], v[170:171], s[60:61]
	v_pk_mul_f32 v[172:173], v[172:173], s[60:61]
	v_pk_mul_f32 v[206:207], v[206:207], s[60:61]
	v_pk_mul_f32 v[210:211], v[210:211], s[60:61]
	v_pk_mul_f32 v[244:245], v[244:245], s[60:61]
	v_pk_mul_f32 v[248:249], v[248:249], s[60:61]
	v_pk_mul_f32 v[250:251], v[250:251], s[60:61]
	v_exp_f32_e32 v164, v164
	v_exp_f32_e32 v170, v170
	v_exp_f32_e32 v172, v172
	v_exp_f32_e32 v206, v206
	v_exp_f32_e32 v165, v165
	v_exp_f32_e32 v171, v171
	v_exp_f32_e32 v173, v173
	v_exp_f32_e32 v207, v207
	v_exp_f32_e32 v210, v210
	v_exp_f32_e32 v244, v244
	v_exp_f32_e32 v248, v248
	v_exp_f32_e32 v250, v250
	v_exp_f32_e32 v211, v211
	v_exp_f32_e32 v245, v245
	v_exp_f32_e32 v249, v249
	v_exp_f32_e32 v251, v251
	v_pk_add_f32 v[164:165], v[164:165], s[78:79]
	v_pk_add_f32 v[170:171], v[170:171], s[78:79]
	v_pk_add_f32 v[172:173], v[172:173], s[78:79]
	v_pk_add_f32 v[206:207], v[206:207], s[78:79]
	v_pk_add_f32 v[210:211], v[210:211], s[78:79]
	v_pk_add_f32 v[244:245], v[244:245], s[78:79]
	v_pk_add_f32 v[248:249], v[248:249], s[78:79]
	v_pk_add_f32 v[250:251], v[250:251], s[78:79]
	v_rcp_f32_e32 v164, v164
	v_rcp_f32_e32 v170, v170
	v_rcp_f32_e32 v172, v172
	v_rcp_f32_e32 v206, v206
	v_rcp_f32_e32 v165, v165
	v_rcp_f32_e32 v171, v171
	v_rcp_f32_e32 v173, v173
	v_rcp_f32_e32 v207, v207
	s_nop 0
	v_pk_mul_f32 v[164:165], v[164:165], v[210:211]
	v_pk_mul_f32 v[170:171], v[170:171], v[244:245]
	v_pk_mul_f32 v[172:173], v[172:173], v[248:249]
	v_pk_mul_f32 v[206:207], v[206:207], v[250:251]
	v_pk_mul_f32 v[76:77], v[76:77], v[164:165]
	v_pk_mul_f32 v[78:79], v[78:79], v[170:171]
	v_pk_mul_f32 v[72:73], v[72:73], v[172:173]
	v_pk_mul_f32 v[74:75], v[74:75], v[206:207]
	s_add_u32 s8, s24, 0x16000
	s_addc_u32 s9, s25, 0
	global_load_dwordx4 v[232:235], v216, s[8:9]
	s_add_u32 s8, s24, 0x96000
	s_addc_u32 s9, s25, 0
	global_load_dwordx4 v[202:205], v216, s[8:9]
	s_waitcnt vmcnt(14)
	s_add_u32 s98, s26, 0x18000
	s_addc_u32 s99, s27, 0
	v_lshlrev_b32_e32 v164, 16, v236
	v_lshlrev_b32_e32 v170, 16, v237
	v_lshlrev_b32_e32 v172, 16, v238
	v_lshlrev_b32_e32 v206, 16, v239
	v_and_b32_e32 v165, 0xffff0000, v236
	v_and_b32_e32 v171, 0xffff0000, v237
	v_and_b32_e32 v173, 0xffff0000, v238
	v_and_b32_e32 v207, 0xffff0000, v239
	v_lshlrev_b32_e32 v210, 16, v240
	v_lshlrev_b32_e32 v244, 16, v241
	v_lshlrev_b32_e32 v248, 16, v242
	v_lshlrev_b32_e32 v250, 16, v243
	v_and_b32_e32 v211, 0xffff0000, v240
	v_and_b32_e32 v245, 0xffff0000, v241
	v_and_b32_e32 v249, 0xffff0000, v242
	v_and_b32_e32 v251, 0xffff0000, v243
	v_pk_mul_f32 v[164:165], v[164:165], s[60:61]
	v_pk_mul_f32 v[170:171], v[170:171], s[60:61]
	v_pk_mul_f32 v[172:173], v[172:173], s[60:61]
	v_pk_mul_f32 v[206:207], v[206:207], s[60:61]
	v_pk_mul_f32 v[210:211], v[210:211], s[60:61]
	v_pk_mul_f32 v[244:245], v[244:245], s[60:61]
	v_pk_mul_f32 v[248:249], v[248:249], s[60:61]
	v_pk_mul_f32 v[250:251], v[250:251], s[60:61]
	v_exp_f32_e32 v164, v164
	v_exp_f32_e32 v170, v170
	v_exp_f32_e32 v172, v172
	v_exp_f32_e32 v206, v206
	v_exp_f32_e32 v165, v165
	v_exp_f32_e32 v171, v171
	v_exp_f32_e32 v173, v173
	v_exp_f32_e32 v207, v207
	v_exp_f32_e32 v210, v210
	v_exp_f32_e32 v244, v244
	v_exp_f32_e32 v248, v248
	v_exp_f32_e32 v250, v250
	v_exp_f32_e32 v211, v211
	v_exp_f32_e32 v245, v245
	v_exp_f32_e32 v249, v249
	v_exp_f32_e32 v251, v251
	v_pk_add_f32 v[164:165], v[164:165], s[78:79]
	v_pk_add_f32 v[170:171], v[170:171], s[78:79]
	v_pk_add_f32 v[172:173], v[172:173], s[78:79]
	v_pk_add_f32 v[206:207], v[206:207], s[78:79]
	v_pk_add_f32 v[210:211], v[210:211], s[78:79]
	v_pk_add_f32 v[244:245], v[244:245], s[78:79]
	v_pk_add_f32 v[248:249], v[248:249], s[78:79]
	v_pk_add_f32 v[250:251], v[250:251], s[78:79]
	v_rcp_f32_e32 v164, v164
	v_rcp_f32_e32 v170, v170
	v_rcp_f32_e32 v172, v172
	v_rcp_f32_e32 v206, v206
	v_rcp_f32_e32 v165, v165
	v_rcp_f32_e32 v171, v171
	v_rcp_f32_e32 v173, v173
	v_rcp_f32_e32 v207, v207
	s_nop 0
	v_pk_mul_f32 v[164:165], v[164:165], v[210:211]
	v_pk_mul_f32 v[170:171], v[170:171], v[244:245]
	v_pk_mul_f32 v[172:173], v[172:173], v[248:249]
	v_pk_mul_f32 v[206:207], v[206:207], v[250:251]
	v_pk_mul_f32 v[68:69], v[68:69], v[164:165]
	v_pk_mul_f32 v[70:71], v[70:71], v[170:171]
	v_pk_mul_f32 v[64:65], v[64:65], v[172:173]
	v_pk_mul_f32 v[66:67], v[66:67], v[206:207]
	s_add_u32 s8, s24, 0x16000
	s_addc_u32 s9, s25, 0
	global_load_dwordx4 v[236:239], v216, s[8:9] offset:256
	s_add_u32 s8, s24, 0x96000
	s_addc_u32 s9, s25, 0
	global_load_dwordx4 v[240:243], v216, s[8:9] offset:256
	s_waitcnt vmcnt(14)
	s_add_u32 s98, s26, 0x40000
	s_addc_u32 s99, s27, 0
	v_lshlrev_b32_e32 v164, 16, v132
	v_lshlrev_b32_e32 v170, 16, v133
	v_lshlrev_b32_e32 v172, 16, v134
	v_lshlrev_b32_e32 v206, 16, v135
	v_and_b32_e32 v165, 0xffff0000, v132
	v_and_b32_e32 v171, 0xffff0000, v133
	v_and_b32_e32 v173, 0xffff0000, v134
	v_and_b32_e32 v207, 0xffff0000, v135
	v_lshlrev_b32_e32 v210, 16, v148
	v_lshlrev_b32_e32 v244, 16, v149
	v_lshlrev_b32_e32 v248, 16, v150
	v_lshlrev_b32_e32 v250, 16, v151
	v_and_b32_e32 v211, 0xffff0000, v148
	v_and_b32_e32 v245, 0xffff0000, v149
	v_and_b32_e32 v249, 0xffff0000, v150
	v_and_b32_e32 v251, 0xffff0000, v151
	v_pk_mul_f32 v[164:165], v[164:165], s[60:61]
	v_pk_mul_f32 v[170:171], v[170:171], s[60:61]
	v_pk_mul_f32 v[172:173], v[172:173], s[60:61]
	v_pk_mul_f32 v[206:207], v[206:207], s[60:61]
	v_pk_mul_f32 v[210:211], v[210:211], s[60:61]
	v_pk_mul_f32 v[244:245], v[244:245], s[60:61]
	v_pk_mul_f32 v[248:249], v[248:249], s[60:61]
	v_pk_mul_f32 v[250:251], v[250:251], s[60:61]
	v_exp_f32_e32 v164, v164
	v_exp_f32_e32 v170, v170
	v_exp_f32_e32 v172, v172
	v_exp_f32_e32 v206, v206
	v_exp_f32_e32 v165, v165
	v_exp_f32_e32 v171, v171
	v_exp_f32_e32 v173, v173
	v_exp_f32_e32 v207, v207
	v_exp_f32_e32 v210, v210
	v_exp_f32_e32 v244, v244
	v_exp_f32_e32 v248, v248
	v_exp_f32_e32 v250, v250
	v_exp_f32_e32 v211, v211
	v_exp_f32_e32 v245, v245
	v_exp_f32_e32 v249, v249
	v_exp_f32_e32 v251, v251
	v_pk_add_f32 v[164:165], v[164:165], s[78:79]
	v_pk_add_f32 v[170:171], v[170:171], s[78:79]
	v_pk_add_f32 v[172:173], v[172:173], s[78:79]
	v_pk_add_f32 v[206:207], v[206:207], s[78:79]
	v_pk_add_f32 v[210:211], v[210:211], s[78:79]
	v_pk_add_f32 v[244:245], v[244:245], s[78:79]
	v_pk_add_f32 v[248:249], v[248:249], s[78:79]
	v_pk_add_f32 v[250:251], v[250:251], s[78:79]
	v_rcp_f32_e32 v164, v164
	v_rcp_f32_e32 v170, v170
	v_rcp_f32_e32 v172, v172
	v_rcp_f32_e32 v206, v206
	v_rcp_f32_e32 v165, v165
	v_rcp_f32_e32 v171, v171
	v_rcp_f32_e32 v173, v173
	v_rcp_f32_e32 v207, v207
	s_nop 0
	v_pk_mul_f32 v[164:165], v[164:165], v[210:211]
	v_pk_mul_f32 v[170:171], v[170:171], v[244:245]
	v_pk_mul_f32 v[172:173], v[172:173], v[248:249]
	v_pk_mul_f32 v[206:207], v[206:207], v[250:251]
	v_pk_mul_f32 v[60:61], v[60:61], v[164:165]
	v_pk_mul_f32 v[62:63], v[62:63], v[170:171]
	v_pk_mul_f32 v[56:57], v[56:57], v[172:173]
	v_pk_mul_f32 v[58:59], v[58:59], v[206:207]
	s_waitcnt vmcnt(12)
	s_add_u32 s98, s26, 0x40000
	s_addc_u32 s99, s27, 0
	v_lshlrev_b32_e32 v164, 16, v136
	v_lshlrev_b32_e32 v170, 16, v137
	v_lshlrev_b32_e32 v172, 16, v138
	v_lshlrev_b32_e32 v206, 16, v139
	v_and_b32_e32 v165, 0xffff0000, v136
	v_and_b32_e32 v171, 0xffff0000, v137
	v_and_b32_e32 v173, 0xffff0000, v138
	v_and_b32_e32 v207, 0xffff0000, v139
	v_lshlrev_b32_e32 v210, 16, v152
	v_lshlrev_b32_e32 v244, 16, v153
	v_lshlrev_b32_e32 v248, 16, v154
	v_lshlrev_b32_e32 v250, 16, v155
	v_and_b32_e32 v211, 0xffff0000, v152
	v_and_b32_e32 v245, 0xffff0000, v153
	v_and_b32_e32 v249, 0xffff0000, v154
	v_and_b32_e32 v251, 0xffff0000, v155
	v_pk_mul_f32 v[164:165], v[164:165], s[60:61]
	v_pk_mul_f32 v[170:171], v[170:171], s[60:61]
	v_pk_mul_f32 v[172:173], v[172:173], s[60:61]
	v_pk_mul_f32 v[206:207], v[206:207], s[60:61]
	v_pk_mul_f32 v[210:211], v[210:211], s[60:61]
	v_pk_mul_f32 v[244:245], v[244:245], s[60:61]
	v_pk_mul_f32 v[248:249], v[248:249], s[60:61]
	v_pk_mul_f32 v[250:251], v[250:251], s[60:61]
	v_exp_f32_e32 v164, v164
	v_exp_f32_e32 v170, v170
	v_exp_f32_e32 v172, v172
	v_exp_f32_e32 v206, v206
	v_exp_f32_e32 v165, v165
	v_exp_f32_e32 v171, v171
	v_exp_f32_e32 v173, v173
	v_exp_f32_e32 v207, v207
	v_exp_f32_e32 v210, v210
	v_exp_f32_e32 v244, v244
	v_exp_f32_e32 v248, v248
	v_exp_f32_e32 v250, v250
	v_exp_f32_e32 v211, v211
	v_exp_f32_e32 v245, v245
	v_exp_f32_e32 v249, v249
	v_exp_f32_e32 v251, v251
	v_pk_add_f32 v[164:165], v[164:165], s[78:79]
	v_pk_add_f32 v[170:171], v[170:171], s[78:79]
	v_pk_add_f32 v[172:173], v[172:173], s[78:79]
	v_pk_add_f32 v[206:207], v[206:207], s[78:79]
	v_pk_add_f32 v[210:211], v[210:211], s[78:79]
	v_pk_add_f32 v[244:245], v[244:245], s[78:79]
	v_pk_add_f32 v[248:249], v[248:249], s[78:79]
	v_pk_add_f32 v[250:251], v[250:251], s[78:79]
	v_rcp_f32_e32 v164, v164
	v_rcp_f32_e32 v170, v170
	v_rcp_f32_e32 v172, v172
	v_rcp_f32_e32 v206, v206
	v_rcp_f32_e32 v165, v165
	v_rcp_f32_e32 v171, v171
	v_rcp_f32_e32 v173, v173
	v_rcp_f32_e32 v207, v207
	s_nop 0
	v_pk_mul_f32 v[164:165], v[164:165], v[210:211]
	v_pk_mul_f32 v[170:171], v[170:171], v[244:245]
	v_pk_mul_f32 v[172:173], v[172:173], v[248:249]
	v_pk_mul_f32 v[206:207], v[206:207], v[250:251]
	v_pk_mul_f32 v[52:53], v[52:53], v[164:165]
	v_pk_mul_f32 v[54:55], v[54:55], v[170:171]
	v_pk_mul_f32 v[48:49], v[48:49], v[172:173]
	v_pk_mul_f32 v[50:51], v[50:51], v[206:207]
	s_waitcnt vmcnt(10)
	s_add_u32 s98, s26, 0x48000
	s_addc_u32 s99, s27, 0
	v_lshlrev_b32_e32 v164, 16, v140
	v_lshlrev_b32_e32 v170, 16, v141
	v_lshlrev_b32_e32 v172, 16, v142
	v_lshlrev_b32_e32 v206, 16, v143
	v_and_b32_e32 v165, 0xffff0000, v140
	v_and_b32_e32 v171, 0xffff0000, v141
	v_and_b32_e32 v173, 0xffff0000, v142
	v_and_b32_e32 v207, 0xffff0000, v143
	v_lshlrev_b32_e32 v210, 16, v156
	v_lshlrev_b32_e32 v244, 16, v157
	v_lshlrev_b32_e32 v248, 16, v158
	v_lshlrev_b32_e32 v250, 16, v159
	v_and_b32_e32 v211, 0xffff0000, v156
	v_and_b32_e32 v245, 0xffff0000, v157
	v_and_b32_e32 v249, 0xffff0000, v158
	v_and_b32_e32 v251, 0xffff0000, v159
	v_pk_mul_f32 v[164:165], v[164:165], s[60:61]
	v_pk_mul_f32 v[170:171], v[170:171], s[60:61]
	v_pk_mul_f32 v[172:173], v[172:173], s[60:61]
	v_pk_mul_f32 v[206:207], v[206:207], s[60:61]
	v_pk_mul_f32 v[210:211], v[210:211], s[60:61]
	v_pk_mul_f32 v[244:245], v[244:245], s[60:61]
	v_pk_mul_f32 v[248:249], v[248:249], s[60:61]
	v_pk_mul_f32 v[250:251], v[250:251], s[60:61]
	v_exp_f32_e32 v164, v164
	v_exp_f32_e32 v170, v170
	v_exp_f32_e32 v172, v172
	v_exp_f32_e32 v206, v206
	v_exp_f32_e32 v165, v165
	v_exp_f32_e32 v171, v171
	v_exp_f32_e32 v173, v173
	v_exp_f32_e32 v207, v207
	v_exp_f32_e32 v210, v210
	v_exp_f32_e32 v244, v244
	v_exp_f32_e32 v248, v248
	v_exp_f32_e32 v250, v250
	v_exp_f32_e32 v211, v211
	v_exp_f32_e32 v245, v245
	v_exp_f32_e32 v249, v249
	v_exp_f32_e32 v251, v251
	v_pk_add_f32 v[164:165], v[164:165], s[78:79]
	v_pk_add_f32 v[170:171], v[170:171], s[78:79]
	v_pk_add_f32 v[172:173], v[172:173], s[78:79]
	v_pk_add_f32 v[206:207], v[206:207], s[78:79]
	v_pk_add_f32 v[210:211], v[210:211], s[78:79]
	v_pk_add_f32 v[244:245], v[244:245], s[78:79]
	v_pk_add_f32 v[248:249], v[248:249], s[78:79]
	v_pk_add_f32 v[250:251], v[250:251], s[78:79]
	v_rcp_f32_e32 v164, v164
	v_rcp_f32_e32 v170, v170
	v_rcp_f32_e32 v172, v172
	v_rcp_f32_e32 v206, v206
	v_rcp_f32_e32 v165, v165
	v_rcp_f32_e32 v171, v171
	v_rcp_f32_e32 v173, v173
	v_rcp_f32_e32 v207, v207
	s_nop 0
	v_pk_mul_f32 v[164:165], v[164:165], v[210:211]
	v_pk_mul_f32 v[170:171], v[170:171], v[244:245]
	v_pk_mul_f32 v[172:173], v[172:173], v[248:249]
	v_pk_mul_f32 v[206:207], v[206:207], v[250:251]
	v_pk_mul_f32 v[44:45], v[44:45], v[164:165]
	v_pk_mul_f32 v[46:47], v[46:47], v[170:171]
	v_pk_mul_f32 v[40:41], v[40:41], v[172:173]
	v_pk_mul_f32 v[42:43], v[42:43], v[206:207]
	s_waitcnt vmcnt(8)
	s_add_u32 s98, s26, 0x48000
	s_addc_u32 s99, s27, 0
	v_lshlrev_b32_e32 v164, 16, v144
	v_lshlrev_b32_e32 v170, 16, v145
	v_lshlrev_b32_e32 v172, 16, v146
	v_lshlrev_b32_e32 v206, 16, v147
	v_and_b32_e32 v165, 0xffff0000, v144
	v_and_b32_e32 v171, 0xffff0000, v145
	v_and_b32_e32 v173, 0xffff0000, v146
	v_and_b32_e32 v207, 0xffff0000, v147
	v_lshlrev_b32_e32 v210, 16, v160
	v_lshlrev_b32_e32 v244, 16, v161
	v_lshlrev_b32_e32 v248, 16, v162
	v_lshlrev_b32_e32 v250, 16, v163
	v_and_b32_e32 v211, 0xffff0000, v160
	v_and_b32_e32 v245, 0xffff0000, v161
	v_and_b32_e32 v249, 0xffff0000, v162
	v_and_b32_e32 v251, 0xffff0000, v163
	v_pk_mul_f32 v[164:165], v[164:165], s[60:61]
	v_pk_mul_f32 v[170:171], v[170:171], s[60:61]
	v_pk_mul_f32 v[172:173], v[172:173], s[60:61]
	v_pk_mul_f32 v[206:207], v[206:207], s[60:61]
	v_pk_mul_f32 v[210:211], v[210:211], s[60:61]
	v_pk_mul_f32 v[244:245], v[244:245], s[60:61]
	v_pk_mul_f32 v[248:249], v[248:249], s[60:61]
	v_pk_mul_f32 v[250:251], v[250:251], s[60:61]
	v_exp_f32_e32 v164, v164
	v_exp_f32_e32 v170, v170
	v_exp_f32_e32 v172, v172
	v_exp_f32_e32 v206, v206
	v_exp_f32_e32 v165, v165
	v_exp_f32_e32 v171, v171
	v_exp_f32_e32 v173, v173
	v_exp_f32_e32 v207, v207
	v_exp_f32_e32 v210, v210
	v_exp_f32_e32 v244, v244
	v_exp_f32_e32 v248, v248
	v_exp_f32_e32 v250, v250
	v_exp_f32_e32 v211, v211
	v_exp_f32_e32 v245, v245
	v_exp_f32_e32 v249, v249
	v_exp_f32_e32 v251, v251
	v_pk_add_f32 v[164:165], v[164:165], s[78:79]
	v_pk_add_f32 v[170:171], v[170:171], s[78:79]
	v_pk_add_f32 v[172:173], v[172:173], s[78:79]
	v_pk_add_f32 v[206:207], v[206:207], s[78:79]
	v_pk_add_f32 v[210:211], v[210:211], s[78:79]
	v_pk_add_f32 v[244:245], v[244:245], s[78:79]
	v_pk_add_f32 v[248:249], v[248:249], s[78:79]
	v_pk_add_f32 v[250:251], v[250:251], s[78:79]
	v_rcp_f32_e32 v164, v164
	v_rcp_f32_e32 v170, v170
	v_rcp_f32_e32 v172, v172
	v_rcp_f32_e32 v206, v206
	v_rcp_f32_e32 v165, v165
	v_rcp_f32_e32 v171, v171
	v_rcp_f32_e32 v173, v173
	v_rcp_f32_e32 v207, v207
	s_nop 0
	v_pk_mul_f32 v[164:165], v[164:165], v[210:211]
	v_pk_mul_f32 v[170:171], v[170:171], v[244:245]
	v_pk_mul_f32 v[172:173], v[172:173], v[248:249]
	v_pk_mul_f32 v[206:207], v[206:207], v[250:251]
	v_pk_mul_f32 v[36:37], v[36:37], v[164:165]
	v_pk_mul_f32 v[38:39], v[38:39], v[170:171]
	v_pk_mul_f32 v[32:33], v[32:33], v[172:173]
	v_pk_mul_f32 v[34:35], v[34:35], v[206:207]
	s_waitcnt vmcnt(6)
	s_add_u32 s98, s26, 0x50000
	s_addc_u32 s99, s27, 0
	v_lshlrev_b32_e32 v164, 16, v224
	v_lshlrev_b32_e32 v170, 16, v225
	v_lshlrev_b32_e32 v172, 16, v226
	v_lshlrev_b32_e32 v206, 16, v227
	v_and_b32_e32 v165, 0xffff0000, v224
	v_and_b32_e32 v171, 0xffff0000, v225
	v_and_b32_e32 v173, 0xffff0000, v226
	v_and_b32_e32 v207, 0xffff0000, v227
	v_lshlrev_b32_e32 v210, 16, v194
	v_lshlrev_b32_e32 v244, 16, v195
	v_lshlrev_b32_e32 v248, 16, v196
	v_lshlrev_b32_e32 v250, 16, v197
	v_and_b32_e32 v211, 0xffff0000, v194
	v_and_b32_e32 v245, 0xffff0000, v195
	v_and_b32_e32 v249, 0xffff0000, v196
	v_and_b32_e32 v251, 0xffff0000, v197
	v_pk_mul_f32 v[164:165], v[164:165], s[60:61]
	v_pk_mul_f32 v[170:171], v[170:171], s[60:61]
	v_pk_mul_f32 v[172:173], v[172:173], s[60:61]
	v_pk_mul_f32 v[206:207], v[206:207], s[60:61]
	v_pk_mul_f32 v[210:211], v[210:211], s[60:61]
	v_pk_mul_f32 v[244:245], v[244:245], s[60:61]
	v_pk_mul_f32 v[248:249], v[248:249], s[60:61]
	v_pk_mul_f32 v[250:251], v[250:251], s[60:61]
	v_exp_f32_e32 v164, v164
	v_exp_f32_e32 v170, v170
	v_exp_f32_e32 v172, v172
	v_exp_f32_e32 v206, v206
	v_exp_f32_e32 v165, v165
	v_exp_f32_e32 v171, v171
	v_exp_f32_e32 v173, v173
	v_exp_f32_e32 v207, v207
	v_exp_f32_e32 v210, v210
	v_exp_f32_e32 v244, v244
	v_exp_f32_e32 v248, v248
	v_exp_f32_e32 v250, v250
	v_exp_f32_e32 v211, v211
	v_exp_f32_e32 v245, v245
	v_exp_f32_e32 v249, v249
	v_exp_f32_e32 v251, v251
	v_pk_add_f32 v[164:165], v[164:165], s[78:79]
	v_pk_add_f32 v[170:171], v[170:171], s[78:79]
	v_pk_add_f32 v[172:173], v[172:173], s[78:79]
	v_pk_add_f32 v[206:207], v[206:207], s[78:79]
	v_pk_add_f32 v[210:211], v[210:211], s[78:79]
	v_pk_add_f32 v[244:245], v[244:245], s[78:79]
	v_pk_add_f32 v[248:249], v[248:249], s[78:79]
	v_pk_add_f32 v[250:251], v[250:251], s[78:79]
	v_rcp_f32_e32 v164, v164
	v_rcp_f32_e32 v170, v170
	v_rcp_f32_e32 v172, v172
	v_rcp_f32_e32 v206, v206
	v_rcp_f32_e32 v165, v165
	v_rcp_f32_e32 v171, v171
	v_rcp_f32_e32 v173, v173
	v_rcp_f32_e32 v207, v207
	s_nop 0
	v_pk_mul_f32 v[164:165], v[164:165], v[210:211]
	v_pk_mul_f32 v[170:171], v[170:171], v[244:245]
	v_pk_mul_f32 v[172:173], v[172:173], v[248:249]
	v_pk_mul_f32 v[206:207], v[206:207], v[250:251]
	v_pk_mul_f32 v[28:29], v[28:29], v[164:165]
	v_pk_mul_f32 v[30:31], v[30:31], v[170:171]
	v_pk_mul_f32 v[24:25], v[24:25], v[172:173]
	v_pk_mul_f32 v[26:27], v[26:27], v[206:207]
	s_waitcnt vmcnt(4)
	s_add_u32 s98, s26, 0x50000
	s_addc_u32 s99, s27, 0
	v_lshlrev_b32_e32 v164, 16, v228
	v_lshlrev_b32_e32 v170, 16, v229
	v_lshlrev_b32_e32 v172, 16, v230
	v_lshlrev_b32_e32 v206, 16, v231
	v_and_b32_e32 v165, 0xffff0000, v228
	v_and_b32_e32 v171, 0xffff0000, v229
	v_and_b32_e32 v173, 0xffff0000, v230
	v_and_b32_e32 v207, 0xffff0000, v231
	v_lshlrev_b32_e32 v210, 16, v198
	v_lshlrev_b32_e32 v244, 16, v199
	v_lshlrev_b32_e32 v248, 16, v200
	v_lshlrev_b32_e32 v250, 16, v201
	v_and_b32_e32 v211, 0xffff0000, v198
	v_and_b32_e32 v245, 0xffff0000, v199
	v_and_b32_e32 v249, 0xffff0000, v200
	v_and_b32_e32 v251, 0xffff0000, v201
	v_pk_mul_f32 v[164:165], v[164:165], s[60:61]
	v_pk_mul_f32 v[170:171], v[170:171], s[60:61]
	v_pk_mul_f32 v[172:173], v[172:173], s[60:61]
	v_pk_mul_f32 v[206:207], v[206:207], s[60:61]
	v_pk_mul_f32 v[210:211], v[210:211], s[60:61]
	v_pk_mul_f32 v[244:245], v[244:245], s[60:61]
	v_pk_mul_f32 v[248:249], v[248:249], s[60:61]
	v_pk_mul_f32 v[250:251], v[250:251], s[60:61]
	v_exp_f32_e32 v164, v164
	v_exp_f32_e32 v170, v170
	v_exp_f32_e32 v172, v172
	v_exp_f32_e32 v206, v206
	v_exp_f32_e32 v165, v165
	v_exp_f32_e32 v171, v171
	v_exp_f32_e32 v173, v173
	v_exp_f32_e32 v207, v207
	v_exp_f32_e32 v210, v210
	v_exp_f32_e32 v244, v244
	v_exp_f32_e32 v248, v248
	v_exp_f32_e32 v250, v250
	v_exp_f32_e32 v211, v211
	v_exp_f32_e32 v245, v245
	v_exp_f32_e32 v249, v249
	v_exp_f32_e32 v251, v251
	v_pk_add_f32 v[164:165], v[164:165], s[78:79]
	v_pk_add_f32 v[170:171], v[170:171], s[78:79]
	v_pk_add_f32 v[172:173], v[172:173], s[78:79]
	v_pk_add_f32 v[206:207], v[206:207], s[78:79]
	v_pk_add_f32 v[210:211], v[210:211], s[78:79]
	v_pk_add_f32 v[244:245], v[244:245], s[78:79]
	v_pk_add_f32 v[248:249], v[248:249], s[78:79]
	v_pk_add_f32 v[250:251], v[250:251], s[78:79]
	v_rcp_f32_e32 v164, v164
	v_rcp_f32_e32 v170, v170
	v_rcp_f32_e32 v172, v172
	v_rcp_f32_e32 v206, v206
	v_rcp_f32_e32 v165, v165
	v_rcp_f32_e32 v171, v171
	v_rcp_f32_e32 v173, v173
	v_rcp_f32_e32 v207, v207
	s_nop 0
	v_pk_mul_f32 v[164:165], v[164:165], v[210:211]
	v_pk_mul_f32 v[170:171], v[170:171], v[244:245]
	v_pk_mul_f32 v[172:173], v[172:173], v[248:249]
	v_pk_mul_f32 v[206:207], v[206:207], v[250:251]
	v_pk_mul_f32 v[20:21], v[20:21], v[164:165]
	v_pk_mul_f32 v[22:23], v[22:23], v[170:171]
	v_pk_mul_f32 v[16:17], v[16:17], v[172:173]
	v_pk_mul_f32 v[18:19], v[18:19], v[206:207]
	s_waitcnt vmcnt(2)
	s_add_u32 s98, s26, 0x58000
	s_addc_u32 s99, s27, 0
	v_lshlrev_b32_e32 v164, 16, v232
	v_lshlrev_b32_e32 v170, 16, v233
	v_lshlrev_b32_e32 v172, 16, v234
	v_lshlrev_b32_e32 v206, 16, v235
	v_and_b32_e32 v165, 0xffff0000, v232
	v_and_b32_e32 v171, 0xffff0000, v233
	v_and_b32_e32 v173, 0xffff0000, v234
	v_and_b32_e32 v207, 0xffff0000, v235
	v_lshlrev_b32_e32 v210, 16, v202
	v_lshlrev_b32_e32 v244, 16, v203
	v_lshlrev_b32_e32 v248, 16, v204
	v_lshlrev_b32_e32 v250, 16, v205
	v_and_b32_e32 v211, 0xffff0000, v202
	v_and_b32_e32 v245, 0xffff0000, v203
	v_and_b32_e32 v249, 0xffff0000, v204
	v_and_b32_e32 v251, 0xffff0000, v205
	v_pk_mul_f32 v[164:165], v[164:165], s[60:61]
	v_pk_mul_f32 v[170:171], v[170:171], s[60:61]
	v_pk_mul_f32 v[172:173], v[172:173], s[60:61]
	v_pk_mul_f32 v[206:207], v[206:207], s[60:61]
	v_pk_mul_f32 v[210:211], v[210:211], s[60:61]
	v_pk_mul_f32 v[244:245], v[244:245], s[60:61]
	v_pk_mul_f32 v[248:249], v[248:249], s[60:61]
	v_pk_mul_f32 v[250:251], v[250:251], s[60:61]
	v_exp_f32_e32 v164, v164
	v_exp_f32_e32 v170, v170
	v_exp_f32_e32 v172, v172
	v_exp_f32_e32 v206, v206
	v_exp_f32_e32 v165, v165
	v_exp_f32_e32 v171, v171
	v_exp_f32_e32 v173, v173
	v_exp_f32_e32 v207, v207
	v_exp_f32_e32 v210, v210
	v_exp_f32_e32 v244, v244
	v_exp_f32_e32 v248, v248
	v_exp_f32_e32 v250, v250
	v_exp_f32_e32 v211, v211
	v_exp_f32_e32 v245, v245
	v_exp_f32_e32 v249, v249
	v_exp_f32_e32 v251, v251
	v_pk_add_f32 v[164:165], v[164:165], s[78:79]
	v_pk_add_f32 v[170:171], v[170:171], s[78:79]
	v_pk_add_f32 v[172:173], v[172:173], s[78:79]
	v_pk_add_f32 v[206:207], v[206:207], s[78:79]
	v_pk_add_f32 v[210:211], v[210:211], s[78:79]
	v_pk_add_f32 v[244:245], v[244:245], s[78:79]
	v_pk_add_f32 v[248:249], v[248:249], s[78:79]
	v_pk_add_f32 v[250:251], v[250:251], s[78:79]
	v_rcp_f32_e32 v164, v164
	v_rcp_f32_e32 v170, v170
	v_rcp_f32_e32 v172, v172
	v_rcp_f32_e32 v206, v206
	v_rcp_f32_e32 v165, v165
	v_rcp_f32_e32 v171, v171
	v_rcp_f32_e32 v173, v173
	v_rcp_f32_e32 v207, v207
	s_nop 0
	v_pk_mul_f32 v[164:165], v[164:165], v[210:211]
	v_pk_mul_f32 v[170:171], v[170:171], v[244:245]
	v_pk_mul_f32 v[172:173], v[172:173], v[248:249]
	v_pk_mul_f32 v[206:207], v[206:207], v[250:251]
	v_pk_mul_f32 v[12:13], v[12:13], v[164:165]
	v_pk_mul_f32 v[14:15], v[14:15], v[170:171]
	v_pk_mul_f32 v[8:9], v[8:9], v[172:173]
	v_pk_mul_f32 v[10:11], v[10:11], v[206:207]
	s_waitcnt vmcnt(0)
	s_add_u32 s98, s26, 0x58000
	s_addc_u32 s99, s27, 0
	v_lshlrev_b32_e32 v164, 16, v236
	v_lshlrev_b32_e32 v170, 16, v237
	v_lshlrev_b32_e32 v172, 16, v238
	v_lshlrev_b32_e32 v206, 16, v239
	v_and_b32_e32 v165, 0xffff0000, v236
	v_and_b32_e32 v171, 0xffff0000, v237
	v_and_b32_e32 v173, 0xffff0000, v238
	v_and_b32_e32 v207, 0xffff0000, v239
	v_lshlrev_b32_e32 v210, 16, v240
	v_lshlrev_b32_e32 v244, 16, v241
	v_lshlrev_b32_e32 v248, 16, v242
	v_lshlrev_b32_e32 v250, 16, v243
	v_and_b32_e32 v211, 0xffff0000, v240
	v_and_b32_e32 v245, 0xffff0000, v241
	v_and_b32_e32 v249, 0xffff0000, v242
	v_and_b32_e32 v251, 0xffff0000, v243
	v_pk_mul_f32 v[164:165], v[164:165], s[60:61]
	v_pk_mul_f32 v[170:171], v[170:171], s[60:61]
	v_pk_mul_f32 v[172:173], v[172:173], s[60:61]
	v_pk_mul_f32 v[206:207], v[206:207], s[60:61]
	v_pk_mul_f32 v[210:211], v[210:211], s[60:61]
	v_pk_mul_f32 v[244:245], v[244:245], s[60:61]
	v_pk_mul_f32 v[248:249], v[248:249], s[60:61]
	v_pk_mul_f32 v[250:251], v[250:251], s[60:61]
	v_exp_f32_e32 v164, v164
	v_exp_f32_e32 v170, v170
	v_exp_f32_e32 v172, v172
	v_exp_f32_e32 v206, v206
	v_exp_f32_e32 v165, v165
	v_exp_f32_e32 v171, v171
	v_exp_f32_e32 v173, v173
	v_exp_f32_e32 v207, v207
	v_exp_f32_e32 v210, v210
	v_exp_f32_e32 v244, v244
	v_exp_f32_e32 v248, v248
	v_exp_f32_e32 v250, v250
	v_exp_f32_e32 v211, v211
	v_exp_f32_e32 v245, v245
	v_exp_f32_e32 v249, v249
	v_exp_f32_e32 v251, v251
	v_pk_add_f32 v[164:165], v[164:165], s[78:79]
	v_pk_add_f32 v[170:171], v[170:171], s[78:79]
	v_pk_add_f32 v[172:173], v[172:173], s[78:79]
	v_pk_add_f32 v[206:207], v[206:207], s[78:79]
	v_pk_add_f32 v[210:211], v[210:211], s[78:79]
	v_pk_add_f32 v[244:245], v[244:245], s[78:79]
	v_pk_add_f32 v[248:249], v[248:249], s[78:79]
	v_pk_add_f32 v[250:251], v[250:251], s[78:79]
	v_rcp_f32_e32 v164, v164
	v_rcp_f32_e32 v170, v170
	v_rcp_f32_e32 v172, v172
	v_rcp_f32_e32 v206, v206
	v_rcp_f32_e32 v165, v165
	v_rcp_f32_e32 v171, v171
	v_rcp_f32_e32 v173, v173
	v_rcp_f32_e32 v207, v207
	s_nop 0
	v_pk_mul_f32 v[164:165], v[164:165], v[210:211]
	v_pk_mul_f32 v[170:171], v[170:171], v[244:245]
	v_pk_mul_f32 v[172:173], v[172:173], v[248:249]
	v_pk_mul_f32 v[206:207], v[206:207], v[250:251]
	v_pk_mul_f32 v[4:5], v[4:5], v[164:165]
	v_pk_mul_f32 v[6:7], v[6:7], v[170:171]
	v_pk_mul_f32 v[0:1], v[0:1], v[172:173]
	v_pk_mul_f32 v[2:3], v[2:3], v[206:207]
	s_branch .Lp6e_done
	s_lshl_b32 s9, s46, 2
	s_mul_i32 s8, s48, 49
	s_add_i32 s9, s47, s9
	s_add_i32 s8, s9, s8
	s_add_i32 s8, s8, 29
	v_lshl_add_u32 v196, s48, 8, v169
	s_ashr_i32 s9, s8, 31
	s_lshl_b64 s[8:9], s[8:9], 17
	v_lshlrev_b32_e32 v132, 9, v196
	v_lshl_add_u64 v[198:199], v[188:189], 0, s[8:9]
	v_and_b32_e32 v166, 0x19e00, v132
	v_lshl_add_u64 v[134:135], v[198:199], 0, v[166:167]
	global_load_dwordx4 v[158:161], v[134:135], off
	v_lshl_or_b32 v194, s47, 8, v219
	v_ashrrev_i32_e32 v195, 31, v194
	v_ashrrev_i32_e32 v197, 31, v196
	v_lshl_add_u64 v[200:201], v[194:195], 1, v[176:177]
	s_cmp_gt_i32 s46, 0
	v_lshlrev_b64 v[204:205], 11, v[196:197]
	s_cselect_b64 s[24:25], -1, 0
	s_cmp_lt_i32 s46, 1
	v_lshl_add_u64 v[132:133], v[200:201], 0, v[204:205]
	s_cbranch_scc1 .LBB0_1759
	global_load_dwordx4 v[162:165], v[132:133], off
	s_branch .LBB0_1760

.LBB0_1793:
	s_mov_b64 s[8:9], s[62:63]
	global_load_dwordx2 v[132:133], v167, s[8:9] offset:192
	s_mov_b64 s[8:9], s[62:63]
	global_load_dwordx2 v[134:135], v167, s[8:9] offset:192
	s_mov_b64 s[2:3], 0x23cc2800
	s_mov_b64 s[10:11], s[62:63]
	v_mov_b32_e32 v148, v208
	s_movk_i32 s8, 0x100
	s_waitcnt vmcnt(0)
	v_lshl_add_u64 v[132:133], v[132:133], 0, s[2:3]
	v_readlane_b32 s2, v255, 1
	v_readlane_b32 s3, v255, 2
	v_lshl_add_u64 v[134:135], v[134:135], 0, s[6:7]
	s_mov_b64 s[6:7], 0x3500000
	v_lshl_add_u64 v[134:135], v[134:135], 0, s[6:7]
	s_mov_b64 s[6:7], s[62:63]
	v_readfirstlane_b32 s5, v133
	v_readfirstlane_b32 s24, v132
	v_readfirstlane_b32 s26, v135
	v_readfirstlane_b32 s25, v148
	v_readfirstlane_b32 s27, v134
	s_and_b64 vcc, exec, s[2:3]
	s_cbranch_vccnz .LBB0_1815
	v_lshlrev_b32_e32 v136, 4, v148
	v_add_u32_e32 v137, 0x2000, v136
	v_ashrrev_i32_e32 v138, 31, v137
	v_lshrrev_b32_e32 v138, 22, v138
	v_add_u32_e32 v138, v137, v138
	v_ashrrev_i32_e32 v138, 10, v138
	v_mul_i32_i24_e32 v139, 0x400, v138
	v_sub_u32_e32 v137, v137, v139
	v_lshrrev_b32_e32 v139, 4, v137
	v_bitop3_b32 v137, v139, v137, 32 bitop3:0x6c
	v_ashrrev_i32_e32 v139, 31, v137
	v_lshrrev_b32_e32 v139, 26, v139
	v_add_u32_e32 v139, v137, v139
	v_lshlrev_b32_e32 v141, 3, v138
	v_ashrrev_i32_e32 v140, 6, v139
	v_and_b32_e32 v141, -16, v141
	v_add_u32_e32 v141, v140, v141
	v_and_b32_e32 v140, 3, v140
	s_mov_b32 s0, 0x7fffffe0
	v_lshrrev_b32_e32 v142, 2, v141
	v_lshlrev_b32_e32 v143, 1, v141
	v_lshlrev_b32_e32 v138, 5, v138
	v_and_or_b32 v140, v141, s0, v140
	v_and_b32_e32 v142, 4, v142
	v_and_b32_e32 v143, 24, v143
	v_and_b32_e32 v149, 32, v138
	v_and_b32_e32 v138, 0xc0, v139
	v_or3_b32 v140, v140, v142, v143
	v_sub_u32_e32 v137, v137, v138
	v_mov_b32_e32 v143, 1
	v_ashrrev_i16_sdwa v137, v143, sext(v137) dst_sel:DWORD dst_unused:UNUSED_PAD src0_sel:DWORD src1_sel:BYTE_0
	v_bfe_i32 v150, v137, 0, 16
	v_mul_lo_u32 v140, v140, s8
	v_add_u32_e32 v137, v149, v150
	v_mul_lo_u32 v151, v141, s8
	v_add_lshl_u32 v156, v140, v137, 1
	v_add_lshl_u32 v158, v137, v151, 1
	v_bfe_i32 v137, v148, 27, 1
	v_lshrrev_b32_e32 v137, 22, v137
	v_add_u32_e32 v137, v136, v137
	v_and_b32_e32 v137, 0xfffffc00, v137
	v_sub_u32_e32 v136, v136, v137
	v_ashrrev_i32_e32 v138, 31, v148
	v_lshrrev_b32_e32 v137, 4, v136
	v_lshrrev_b32_e32 v138, 26, v138
	v_bitop3_b32 v137, v137, v136, 32 bitop3:0x6c
	v_ashrrev_i32_e32 v136, 31, v136
	v_add_u32_e32 v138, v148, v138
	v_lshrrev_b32_e32 v136, 26, v136
	v_ashrrev_i32_e32 v138, 6, v138
	v_add_u32_e32 v136, v137, v136
	v_lshlrev_b32_e32 v139, 3, v138
	v_ashrrev_i32_e32 v136, 6, v136
	v_and_b32_e32 v139, -16, v139
	s_ashr_i32 s9, s8, 31
	v_add_u32_e32 v139, v136, v139
	v_and_b32_e32 v140, 3, v136
	s_lshl_b64 s[14:15], s[8:9], 9
	v_and_or_b32 v140, v139, s0, v140
	v_readlane_b32 s0, v253, 46
	v_readlane_b32 s2, v253, 47
	s_mul_i32 s12, s14, s0
	s_mul_hi_u32 s13, s14, s70
	v_readlane_b32 s3, v253, 48
	v_mul_i32_i24_e32 v136, 64, v136
	s_add_i32 s16, s13, s12
	s_lshr_b64 s[12:13], s[8:9], 23
	s_mul_i32 s17, s14, s3
	s_mul_hi_u32 s18, s14, s2
	global_load_dwordx2 v[132:133], v167, s[6:7] offset:192
	global_load_dwordx2 v[134:135], v167, s[10:11] offset:192
	s_ashr_i32 s10, s25, 6
	v_lshrrev_b32_e32 v141, 2, v139
	v_lshlrev_b32_e32 v142, 1, v139
	v_sub_u32_e32 v136, v137, v136
	s_mul_i32 s13, s12, s70
	s_add_i32 s17, s18, s17
	s_mul_i32 s12, s12, s2
	s_ashr_i32 s11, s25, 8
	s_lshl_b64 s[6:7], s[8:9], 8
	s_lshl_b32 s28, s10, 10
	v_and_b32_e32 v141, 4, v141
	v_and_b32_e32 v142, 24, v142
	v_lshlrev_b32_e32 v138, 5, v138
	v_ashrrev_i16_sdwa v136, v143, sext(v136) dst_sel:DWORD dst_unused:UNUSED_PAD src0_sel:DWORD src1_sel:BYTE_0
	s_add_i32 s16, s16, s13
	s_add_i32 s17, s17, s12
	s_mul_i32 s12, s14, s2
	v_or3_b32 v140, v140, v141, v142
	v_and_b32_e32 v152, 32, v138
	v_bfe_i32 v153, v136, 0, 16
	s_add_u32 s18, s27, s12
	v_mul_lo_u32 v140, v140, s8
	v_add_u32_e32 v136, v152, v153
	s_addc_u32 s19, s26, s17
	s_add_i32 s29, s28, 0
	v_add_lshl_u32 v160, v140, v136, 1
	s_add_i32 m0, s29, 0x10000
	s_mul_i32 s13, s14, s70
	global_load_lds_dwordx4 v160, s[18:19]
	s_add_i32 m0, s29, 0x12000
	v_mul_lo_u32 v154, v139, s8
	s_add_u32 s20, s24, s13
	v_add_lshl_u32 v162, v136, v154, 1
	global_load_lds_dwordx4 v156, s[18:19]
	s_addc_u32 s21, s5, s16
	s_mov_b32 m0, s29
	s_add_i32 s30, s29, 0x2000
	global_load_lds_dwordx4 v162, s[20:21]
	s_mov_b32 m0, s30
	s_add_u32 s12, s18, s6
	global_load_lds_dwordx4 v158, s[20:21]
	s_addc_u32 s13, s19, s7
	s_add_i32 m0, s29, 0x14000
	v_mov_b32_e32 v161, v167
	v_mov_b32_e32 v157, v167
	global_load_lds_dwordx4 v160, s[12:13]
	s_add_i32 m0, s29, 0x16000
	v_lshl_add_u64 v[144:145], s[12:13], 0, v[160:161]
	v_lshl_add_u64 v[146:147], s[12:13], 0, v[156:157]
	global_load_lds_dwordx4 v156, s[12:13]
	s_add_u32 s12, s20, s6
	s_addc_u32 s13, s21, s7
	s_add_i32 s31, s29, 0x4000
	s_mov_b32 m0, s31
	s_add_i32 s34, s29, 0x6000
	global_load_lds_dwordx4 v162, s[12:13]
	s_mov_b32 m0, s34
	v_mov_b32_e32 v163, v167
	global_load_lds_dwordx4 v158, s[12:13]
	v_mov_b32_e32 v159, v167
	v_readlane_b32 s2, v253, 3
	v_lshl_add_u64 v[136:137], s[18:19], 0, v[160:161]
	v_lshl_add_u64 v[138:139], s[18:19], 0, v[156:157]
	v_lshl_add_u64 v[140:141], s[20:21], 0, v[162:163]
	v_lshl_add_u64 v[142:143], s[20:21], 0, v[158:159]
	s_cmp_lg_u32 s11, 1
	v_readlane_b32 s3, v253, 4
	s_cbranch_scc1 .LBB0_1796
	s_barrier
.LBB0_1796:
	s_add_i32 m0, s29, 0x18000
	v_lshl_add_u64 v[136:137], v[136:137], 0, s[88:89]
	s_waitcnt vmcnt(4)
	s_barrier
	global_load_lds_dwordx4 v[136:137], off
	v_lshl_add_u64 v[136:137], v[138:139], 0, s[88:89]
	s_add_i32 m0, s29, 0x1a000
	s_add_i32 s35, s29, 0x8000
	global_load_lds_dwordx4 v[136:137], off
	v_lshl_add_u64 v[136:137], v[140:141], 0, s[88:89]
	s_mov_b32 m0, s35
	s_add_i32 s36, s29, 0xa000
	global_load_lds_dwordx4 v[136:137], off
	v_lshl_add_u64 v[136:137], v[142:143], 0, s[88:89]
	s_mov_b32 m0, s36
	s_mov_b64 s[12:13], 0x5300000
	global_load_lds_dwordx4 v[136:137], off
	s_add_i32 m0, s29, 0x1c000
	v_lshl_add_u64 v[136:137], v[144:145], 0, s[88:89]
	global_load_lds_dwordx4 v[136:137], off
	v_lshl_add_u64 v[136:137], v[146:147], 0, s[88:89]
	s_add_i32 m0, s29, 0x1e000
	s_waitcnt vmcnt(0)
	v_lshl_add_u64 v[164:165], v[134:135], 0, s[12:13]
	global_load_lds_dwordx4 v[136:137], off
	v_lshrrev_b32_e32 v135, 1, v148
	s_lshr_b32 s9, s9, 26
	v_and_b32_e32 v135, 24, v135
	v_and_b32_e32 v134, 15, v148
	s_add_i32 s9, s8, s9
	v_lshlrev_b32_e32 v166, 1, v135
	v_lshlrev_b32_e32 v136, 2, v148
	s_ashr_i32 s37, s9, 6
	v_lshl_or_b32 v169, s11, 6, v134
	v_lshl_or_b32 v134, v134, 6, v166
	s_lshl_b32 s9, s11, 13
	v_and_b32_e32 v136, 32, v136
	v_bitop3_b32 v137, v134, s9, v136 bitop3:0xde
	s_lshl_b32 s9, s10, 5
	s_and_b32 s9, s9, 0x60
	s_lshl_b32 s10, s9, 7
	s_cmp_gt_i32 s8, 63
	s_cselect_b64 s[16:17], -1, 0
	s_lshl_b32 s96, s9, 1
	v_lshl_add_u64 v[132:133], v[132:133], 0, s[96:97]
	v_bitop3_b32 v196, v134, s10, v136 bitop3:0xde
	v_lshl_add_u64 v[132:133], v[132:133], 0, v[166:167]
	s_mov_b64 s[10:11], 0x74c2800
	v_lshl_add_u64 v[178:179], v[132:133], 0, s[10:11]
	v_add_u32_e32 v132, v151, v149
	s_waitcnt vmcnt(6)
	v_add_lshl_u32 v166, v132, v150, 1
	v_add_u32_e32 v132, v154, v152
	v_lshl_add_u64 v[180:181], s[6:7], 0, v[166:167]
	v_add_lshl_u32 v166, v132, v153, 1
	s_add_i32 s38, s37, -2
	v_or_b32_e32 v197, s9, v135
	v_lshl_add_u64 v[182:183], s[6:7], 0, v[166:167]
	s_mov_b32 s39, 0
	v_add_u32_e32 v198, 0, v137
	v_readlane_b32 s42, v253, 45
	s_mov_b32 s43, s70
	s_barrier
	s_branch .LBB0_1798
.LBB0_1797:
	s_load_dwordx2 s[98:99], s[62:63], 0xc0
	v_lshrrev_b32_e32 v170, 8, v208
	v_and_b32_e32 v171, 15, v208
	v_lshl_add_u32 v170, v170, 6, v171
	v_bfe_u32 v171, v208, 6, 2
	v_bfe_u32 v172, v208, 4, 2
	v_lshlrev_b32_e32 v171, 6, v171
	v_lshl_add_u32 v171, v172, 4, v171
	v_lshl_add_u32 v216, v170, 9, v171
	v_lshl_add_u32 v166, v170, 11, v171
	s_mul_i32 s0, s43, 49
	s_add_i32 s0, s0, s42
	s_add_i32 s0, s0, 45
	s_lshl_b32 s0, s0, 17
	s_lshl_b32 s32, s43, 19
	s_lshl_b32 s46, s42, 9
	s_add_i32 s32, s32, s46
	s_mov_b32 s60, 0xbfb8aa3b
	s_mov_b32 s61, 0xbfb8aa3b
	s_mov_b32 s78, 1.0
	s_mov_b32 s79, 1.0
	s_waitcnt lgkmcnt(0)
	s_add_u32 s18, s98, 0x74c2800
	s_addc_u32 s19, s99, 0
	s_add_u32 s18, s18, s0
	s_addc_u32 s19, s19, 0
	s_add_u32 s20, s98, 0x244c2800
	s_addc_u32 s21, s99, 0
	s_add_u32 s20, s20, s32
	s_addc_u32 s21, s21, 0
	s_add_u32 s48, s98, 0x5300000
	s_addc_u32 s49, s99, 0
	s_add_u32 s48, s48, s32
	s_addc_u32 s49, s49, 0
	s_add_u32 s42, s18, 0x0
	s_addc_u32 s43, s19, 0
	global_load_dwordx4 v[132:135], v216, s[42:43]
	s_add_u32 s42, s18, 0x0
	s_addc_u32 s43, s19, 0
	global_load_dwordx4 v[136:139], v216, s[42:43] offset:256
	s_add_u32 s42, s18, 0x2000
	s_addc_u32 s43, s19, 0
	global_load_dwordx4 v[140:143], v216, s[42:43]
	s_add_u32 s42, s18, 0x2000
	s_addc_u32 s43, s19, 0
	global_load_dwordx4 v[144:147], v216, s[42:43] offset:256
	s_add_u32 s42, s18, 0x4000
	s_addc_u32 s43, s19, 0
	global_load_dwordx4 v[224:227], v216, s[42:43]
	s_add_u32 s42, s18, 0x4000
	s_addc_u32 s43, s19, 0
	global_load_dwordx4 v[228:231], v216, s[42:43] offset:256
	s_add_u32 s42, s18, 0x6000
	s_addc_u32 s43, s19, 0
	global_load_dwordx4 v[232:235], v216, s[42:43]
	s_add_u32 s42, s18, 0x6000
	s_addc_u32 s43, s19, 0
	global_load_dwordx4 v[236:239], v216, s[42:43] offset:256
	s_waitcnt vmcnt(7)
	s_add_u32 s98, s48, 0x0
	s_addc_u32 s99, s49, 0
	v_lshlrev_b32_e32 v170, 16, v132
	v_lshlrev_b32_e32 v172, 16, v133
	v_lshlrev_b32_e32 v210, 16, v134
	v_lshlrev_b32_e32 v218, 16, v135
	v_and_b32_e32 v171, 0xffff0000, v132
	v_and_b32_e32 v173, 0xffff0000, v133
	v_and_b32_e32 v211, 0xffff0000, v134
	v_and_b32_e32 v219, 0xffff0000, v135
	v_pk_mul_f32 v[170:171], v[170:171], s[60:61]
	v_pk_mul_f32 v[172:173], v[172:173], s[60:61]
	v_pk_mul_f32 v[210:211], v[210:211], s[60:61]
	v_pk_mul_f32 v[218:219], v[218:219], s[60:61]
	v_exp_f32_e32 v170, v170
	v_exp_f32_e32 v172, v172
	v_exp_f32_e32 v210, v210
	v_exp_f32_e32 v218, v218
	v_exp_f32_e32 v171, v171
	v_exp_f32_e32 v173, v173
	v_exp_f32_e32 v211, v211
	v_exp_f32_e32 v219, v219
	v_pk_add_f32 v[170:171], v[170:171], s[78:79]
	v_pk_add_f32 v[172:173], v[172:173], s[78:79]
	v_pk_add_f32 v[210:211], v[210:211], s[78:79]
	v_pk_add_f32 v[218:219], v[218:219], s[78:79]
	v_rcp_f32_e32 v170, v170
	v_rcp_f32_e32 v172, v172
	v_rcp_f32_e32 v210, v210
	v_rcp_f32_e32 v218, v218
	v_rcp_f32_e32 v171, v171
	v_rcp_f32_e32 v173, v173
	v_rcp_f32_e32 v211, v211
	v_rcp_f32_e32 v219, v219
	s_nop 0
	v_pk_mul_f32 v[128:129], v[128:129], v[170:171]
	v_pk_mul_f32 v[130:131], v[130:131], v[172:173]
	v_pk_mul_f32 v[124:125], v[124:125], v[210:211]
	v_pk_mul_f32 v[126:127], v[126:127], v[218:219]
	v_cvt_pk_bf16_f32 v128, v128, v129
	v_cvt_pk_bf16_f32 v129, v130, v131
	v_cvt_pk_bf16_f32 v130, v124, v125
	v_cvt_pk_bf16_f32 v131, v126, v127
	global_store_dwordx4 v166, v[128:131], s[98:99]
	s_add_u32 s42, s18, 0x10000
	s_addc_u32 s43, s19, 0
	global_load_dwordx4 v[132:135], v216, s[42:43]
	s_waitcnt vmcnt(8)
	s_add_u32 s98, s48, 0x0
	s_addc_u32 s99, s49, 0
	v_lshlrev_b32_e32 v170, 16, v136
	v_lshlrev_b32_e32 v172, 16, v137
	v_lshlrev_b32_e32 v210, 16, v138
	v_lshlrev_b32_e32 v218, 16, v139
	v_and_b32_e32 v171, 0xffff0000, v136
	v_and_b32_e32 v173, 0xffff0000, v137
	v_and_b32_e32 v211, 0xffff0000, v138
	v_and_b32_e32 v219, 0xffff0000, v139
	v_pk_mul_f32 v[170:171], v[170:171], s[60:61]
	v_pk_mul_f32 v[172:173], v[172:173], s[60:61]
	v_pk_mul_f32 v[210:211], v[210:211], s[60:61]
	v_pk_mul_f32 v[218:219], v[218:219], s[60:61]
	v_exp_f32_e32 v170, v170
	v_exp_f32_e32 v172, v172
	v_exp_f32_e32 v210, v210
	v_exp_f32_e32 v218, v218
	v_exp_f32_e32 v171, v171
	v_exp_f32_e32 v173, v173
	v_exp_f32_e32 v211, v211
	v_exp_f32_e32 v219, v219
	v_pk_add_f32 v[170:171], v[170:171], s[78:79]
	v_pk_add_f32 v[172:173], v[172:173], s[78:79]
	v_pk_add_f32 v[210:211], v[210:211], s[78:79]
	v_pk_add_f32 v[218:219], v[218:219], s[78:79]
	v_rcp_f32_e32 v170, v170
	v_rcp_f32_e32 v172, v172
	v_rcp_f32_e32 v210, v210
	v_rcp_f32_e32 v218, v218
	v_rcp_f32_e32 v171, v171
	v_rcp_f32_e32 v173, v173
	v_rcp_f32_e32 v211, v211
	v_rcp_f32_e32 v219, v219
	s_nop 0
	v_pk_mul_f32 v[120:121], v[120:121], v[170:171]
	v_pk_mul_f32 v[122:123], v[122:123], v[172:173]
	v_pk_mul_f32 v[116:117], v[116:117], v[210:211]
	v_pk_mul_f32 v[118:119], v[118:119], v[218:219]
	v_cvt_pk_bf16_f32 v120, v120, v121
	v_cvt_pk_bf16_f32 v121, v122, v123
	v_cvt_pk_bf16_f32 v122, v116, v117
	v_cvt_pk_bf16_f32 v123, v118, v119
	global_store_dwordx4 v166, v[120:123], s[98:99] offset:256
	s_add_u32 s42, s18, 0x10000
	s_addc_u32 s43, s19, 0
	global_load_dwordx4 v[136:139], v216, s[42:43] offset:256
	s_waitcnt vmcnt(9)
	s_add_u32 s98, s48, 0x8000
	s_addc_u32 s99, s49, 0
	v_lshlrev_b32_e32 v170, 16, v140
	v_lshlrev_b32_e32 v172, 16, v141
	v_lshlrev_b32_e32 v210, 16, v142
	v_lshlrev_b32_e32 v218, 16, v143
	v_and_b32_e32 v171, 0xffff0000, v140
	v_and_b32_e32 v173, 0xffff0000, v141
	v_and_b32_e32 v211, 0xffff0000, v142
	v_and_b32_e32 v219, 0xffff0000, v143
	v_pk_mul_f32 v[170:171], v[170:171], s[60:61]
	v_pk_mul_f32 v[172:173], v[172:173], s[60:61]
	v_pk_mul_f32 v[210:211], v[210:211], s[60:61]
	v_pk_mul_f32 v[218:219], v[218:219], s[60:61]
	v_exp_f32_e32 v170, v170
	v_exp_f32_e32 v172, v172
	v_exp_f32_e32 v210, v210
	v_exp_f32_e32 v218, v218
	v_exp_f32_e32 v171, v171
	v_exp_f32_e32 v173, v173
	v_exp_f32_e32 v211, v211
	v_exp_f32_e32 v219, v219
	v_pk_add_f32 v[170:171], v[170:171], s[78:79]
	v_pk_add_f32 v[172:173], v[172:173], s[78:79]
	v_pk_add_f32 v[210:211], v[210:211], s[78:79]
	v_pk_add_f32 v[218:219], v[218:219], s[78:79]
	v_rcp_f32_e32 v170, v170
	v_rcp_f32_e32 v172, v172
	v_rcp_f32_e32 v210, v210
	v_rcp_f32_e32 v218, v218
	v_rcp_f32_e32 v171, v171
	v_rcp_f32_e32 v173, v173
	v_rcp_f32_e32 v211, v211
	v_rcp_f32_e32 v219, v219
	s_nop 0
	v_pk_mul_f32 v[112:113], v[112:113], v[170:171]
	v_pk_mul_f32 v[114:115], v[114:115], v[172:173]
	v_pk_mul_f32 v[108:109], v[108:109], v[210:211]
	v_pk_mul_f32 v[110:111], v[110:111], v[218:219]
	v_cvt_pk_bf16_f32 v112, v112, v113
	v_cvt_pk_bf16_f32 v113, v114, v115
	v_cvt_pk_bf16_f32 v114, v108, v109
	v_cvt_pk_bf16_f32 v115, v110, v111
	global_store_dwordx4 v166, v[112:115], s[98:99]
	s_add_u32 s42, s18, 0x12000
	s_addc_u32 s43, s19, 0
	global_load_dwordx4 v[140:143], v216, s[42:43]
	s_waitcnt vmcnt(10)
	s_add_u32 s98, s48, 0x8000
	s_addc_u32 s99, s49, 0
	v_lshlrev_b32_e32 v170, 16, v144
	v_lshlrev_b32_e32 v172, 16, v145
	v_lshlrev_b32_e32 v210, 16, v146
	v_lshlrev_b32_e32 v218, 16, v147
	v_and_b32_e32 v171, 0xffff0000, v144
	v_and_b32_e32 v173, 0xffff0000, v145
	v_and_b32_e32 v211, 0xffff0000, v146
	v_and_b32_e32 v219, 0xffff0000, v147
	v_pk_mul_f32 v[170:171], v[170:171], s[60:61]
	v_pk_mul_f32 v[172:173], v[172:173], s[60:61]
	v_pk_mul_f32 v[210:211], v[210:211], s[60:61]
	v_pk_mul_f32 v[218:219], v[218:219], s[60:61]
	v_exp_f32_e32 v170, v170
	v_exp_f32_e32 v172, v172
	v_exp_f32_e32 v210, v210
	v_exp_f32_e32 v218, v218
	v_exp_f32_e32 v171, v171
	v_exp_f32_e32 v173, v173
	v_exp_f32_e32 v211, v211
	v_exp_f32_e32 v219, v219
	v_pk_add_f32 v[170:171], v[170:171], s[78:79]
	v_pk_add_f32 v[172:173], v[172:173], s[78:79]
	v_pk_add_f32 v[210:211], v[210:211], s[78:79]
	v_pk_add_f32 v[218:219], v[218:219], s[78:79]
	v_rcp_f32_e32 v170, v170
	v_rcp_f32_e32 v172, v172
	v_rcp_f32_e32 v210, v210
	v_rcp_f32_e32 v218, v218
	v_rcp_f32_e32 v171, v171
	v_rcp_f32_e32 v173, v173
	v_rcp_f32_e32 v211, v211
	v_rcp_f32_e32 v219, v219
	s_nop 0
	v_pk_mul_f32 v[104:105], v[104:105], v[170:171]
	v_pk_mul_f32 v[106:107], v[106:107], v[172:173]
	v_pk_mul_f32 v[100:101], v[100:101], v[210:211]
	v_pk_mul_f32 v[102:103], v[102:103], v[218:219]
	v_cvt_pk_bf16_f32 v104, v104, v105
	v_cvt_pk_bf16_f32 v105, v106, v107
	v_cvt_pk_bf16_f32 v106, v100, v101
	v_cvt_pk_bf16_f32 v107, v102, v103
	global_store_dwordx4 v166, v[104:107], s[98:99] offset:256
	s_add_u32 s42, s18, 0x12000
	s_addc_u32 s43, s19, 0
	global_load_dwordx4 v[144:147], v216, s[42:43] offset:256
	s_waitcnt vmcnt(11)
	s_add_u32 s98, s48, 0x10000
	s_addc_u32 s99, s49, 0
	v_lshlrev_b32_e32 v170, 16, v224
	v_lshlrev_b32_e32 v172, 16, v225
	v_lshlrev_b32_e32 v210, 16, v226
	v_lshlrev_b32_e32 v218, 16, v227
	v_and_b32_e32 v171, 0xffff0000, v224
	v_and_b32_e32 v173, 0xffff0000, v225
	v_and_b32_e32 v211, 0xffff0000, v226
	v_and_b32_e32 v219, 0xffff0000, v227
	v_pk_mul_f32 v[170:171], v[170:171], s[60:61]
	v_pk_mul_f32 v[172:173], v[172:173], s[60:61]
	v_pk_mul_f32 v[210:211], v[210:211], s[60:61]
	v_pk_mul_f32 v[218:219], v[218:219], s[60:61]
	v_exp_f32_e32 v170, v170
	v_exp_f32_e32 v172, v172
	v_exp_f32_e32 v210, v210
	v_exp_f32_e32 v218, v218
	v_exp_f32_e32 v171, v171
	v_exp_f32_e32 v173, v173
	v_exp_f32_e32 v211, v211
	v_exp_f32_e32 v219, v219
	v_pk_add_f32 v[170:171], v[170:171], s[78:79]
	v_pk_add_f32 v[172:173], v[172:173], s[78:79]
	v_pk_add_f32 v[210:211], v[210:211], s[78:79]
	v_pk_add_f32 v[218:219], v[218:219], s[78:79]
	v_rcp_f32_e32 v170, v170
	v_rcp_f32_e32 v172, v172
	v_rcp_f32_e32 v210, v210
	v_rcp_f32_e32 v218, v218
	v_rcp_f32_e32 v171, v171
	v_rcp_f32_e32 v173, v173
	v_rcp_f32_e32 v211, v211
	v_rcp_f32_e32 v219, v219
	s_nop 0
	v_pk_mul_f32 v[96:97], v[96:97], v[170:171]
	v_pk_mul_f32 v[98:99], v[98:99], v[172:173]
	v_pk_mul_f32 v[92:93], v[92:93], v[210:211]
	v_pk_mul_f32 v[94:95], v[94:95], v[218:219]
	v_cvt_pk_bf16_f32 v96, v96, v97
	v_cvt_pk_bf16_f32 v97, v98, v99
	v_cvt_pk_bf16_f32 v98, v92, v93
	v_cvt_pk_bf16_f32 v99, v94, v95
	global_store_dwordx4 v166, v[96:99], s[98:99]
	s_add_u32 s42, s18, 0x14000
	s_addc_u32 s43, s19, 0
	global_load_dwordx4 v[224:227], v216, s[42:43]
	s_waitcnt vmcnt(12)
	s_add_u32 s98, s48, 0x10000
	s_addc_u32 s99, s49, 0
	v_lshlrev_b32_e32 v170, 16, v228
	v_lshlrev_b32_e32 v172, 16, v229
	v_lshlrev_b32_e32 v210, 16, v230
	v_lshlrev_b32_e32 v218, 16, v231
	v_and_b32_e32 v171, 0xffff0000, v228
	v_and_b32_e32 v173, 0xffff0000, v229
	v_and_b32_e32 v211, 0xffff0000, v230
	v_and_b32_e32 v219, 0xffff0000, v231
	v_pk_mul_f32 v[170:171], v[170:171], s[60:61]
	v_pk_mul_f32 v[172:173], v[172:173], s[60:61]
	v_pk_mul_f32 v[210:211], v[210:211], s[60:61]
	v_pk_mul_f32 v[218:219], v[218:219], s[60:61]
	v_exp_f32_e32 v170, v170
	v_exp_f32_e32 v172, v172
	v_exp_f32_e32 v210, v210
	v_exp_f32_e32 v218, v218
	v_exp_f32_e32 v171, v171
	v_exp_f32_e32 v173, v173
	v_exp_f32_e32 v211, v211
	v_exp_f32_e32 v219, v219
	v_pk_add_f32 v[170:171], v[170:171], s[78:79]
	v_pk_add_f32 v[172:173], v[172:173], s[78:79]
	v_pk_add_f32 v[210:211], v[210:211], s[78:79]
	v_pk_add_f32 v[218:219], v[218:219], s[78:79]
	v_rcp_f32_e32 v170, v170
	v_rcp_f32_e32 v172, v172
	v_rcp_f32_e32 v210, v210
	v_rcp_f32_e32 v218, v218
	v_rcp_f32_e32 v171, v171
	v_rcp_f32_e32 v173, v173
	v_rcp_f32_e32 v211, v211
	v_rcp_f32_e32 v219, v219
	s_nop 0
	v_pk_mul_f32 v[88:89], v[88:89], v[170:171]
	v_pk_mul_f32 v[90:91], v[90:91], v[172:173]
	v_pk_mul_f32 v[84:85], v[84:85], v[210:211]
	v_pk_mul_f32 v[86:87], v[86:87], v[218:219]
	v_cvt_pk_bf16_f32 v88, v88, v89
	v_cvt_pk_bf16_f32 v89, v90, v91
	v_cvt_pk_bf16_f32 v90, v84, v85
	v_cvt_pk_bf16_f32 v91, v86, v87
	global_store_dwordx4 v166, v[88:91], s[98:99] offset:256
	s_add_u32 s42, s18, 0x14000
	s_addc_u32 s43, s19, 0
	global_load_dwordx4 v[228:231], v216, s[42:43] offset:256
	s_waitcnt vmcnt(13)
	s_add_u32 s98, s48, 0x18000
	s_addc_u32 s99, s49, 0
	v_lshlrev_b32_e32 v170, 16, v232
	v_lshlrev_b32_e32 v172, 16, v233
	v_lshlrev_b32_e32 v210, 16, v234
	v_lshlrev_b32_e32 v218, 16, v235
	v_and_b32_e32 v171, 0xffff0000, v232
	v_and_b32_e32 v173, 0xffff0000, v233
	v_and_b32_e32 v211, 0xffff0000, v234
	v_and_b32_e32 v219, 0xffff0000, v235
	v_pk_mul_f32 v[170:171], v[170:171], s[60:61]
	v_pk_mul_f32 v[172:173], v[172:173], s[60:61]
	v_pk_mul_f32 v[210:211], v[210:211], s[60:61]
	v_pk_mul_f32 v[218:219], v[218:219], s[60:61]
	v_exp_f32_e32 v170, v170
	v_exp_f32_e32 v172, v172
	v_exp_f32_e32 v210, v210
	v_exp_f32_e32 v218, v218
	v_exp_f32_e32 v171, v171
	v_exp_f32_e32 v173, v173
	v_exp_f32_e32 v211, v211
	v_exp_f32_e32 v219, v219
	v_pk_add_f32 v[170:171], v[170:171], s[78:79]
	v_pk_add_f32 v[172:173], v[172:173], s[78:79]
	v_pk_add_f32 v[210:211], v[210:211], s[78:79]
	v_pk_add_f32 v[218:219], v[218:219], s[78:79]
	v_rcp_f32_e32 v170, v170
	v_rcp_f32_e32 v172, v172
	v_rcp_f32_e32 v210, v210
	v_rcp_f32_e32 v218, v218
	v_rcp_f32_e32 v171, v171
	v_rcp_f32_e32 v173, v173
	v_rcp_f32_e32 v211, v211
	v_rcp_f32_e32 v219, v219
	s_nop 0
	v_pk_mul_f32 v[76:77], v[76:77], v[170:171]
	v_pk_mul_f32 v[78:79], v[78:79], v[172:173]
	v_pk_mul_f32 v[72:73], v[72:73], v[210:211]
	v_pk_mul_f32 v[74:75], v[74:75], v[218:219]
	v_cvt_pk_bf16_f32 v76, v76, v77
	v_cvt_pk_bf16_f32 v77, v78, v79
	v_cvt_pk_bf16_f32 v78, v72, v73
	v_cvt_pk_bf16_f32 v79, v74, v75
	global_store_dwordx4 v166, v[76:79], s[98:99]
	s_add_u32 s42, s18, 0x16000
	s_addc_u32 s43, s19, 0
	global_load_dwordx4 v[232:235], v216, s[42:43]
	s_waitcnt vmcnt(14)
	s_add_u32 s98, s48, 0x18000
	s_addc_u32 s99, s49, 0
	v_lshlrev_b32_e32 v170, 16, v236
	v_lshlrev_b32_e32 v172, 16, v237
	v_lshlrev_b32_e32 v210, 16, v238
	v_lshlrev_b32_e32 v218, 16, v239
	v_and_b32_e32 v171, 0xffff0000, v236
	v_and_b32_e32 v173, 0xffff0000, v237
	v_and_b32_e32 v211, 0xffff0000, v238
	v_and_b32_e32 v219, 0xffff0000, v239
	v_pk_mul_f32 v[170:171], v[170:171], s[60:61]
	v_pk_mul_f32 v[172:173], v[172:173], s[60:61]
	v_pk_mul_f32 v[210:211], v[210:211], s[60:61]
	v_pk_mul_f32 v[218:219], v[218:219], s[60:61]
	v_exp_f32_e32 v170, v170
	v_exp_f32_e32 v172, v172
	v_exp_f32_e32 v210, v210
	v_exp_f32_e32 v218, v218
	v_exp_f32_e32 v171, v171
	v_exp_f32_e32 v173, v173
	v_exp_f32_e32 v211, v211
	v_exp_f32_e32 v219, v219
	v_pk_add_f32 v[170:171], v[170:171], s[78:79]
	v_pk_add_f32 v[172:173], v[172:173], s[78:79]
	v_pk_add_f32 v[210:211], v[210:211], s[78:79]
	v_pk_add_f32 v[218:219], v[218:219], s[78:79]
	v_rcp_f32_e32 v170, v170
	v_rcp_f32_e32 v172, v172
	v_rcp_f32_e32 v210, v210
	v_rcp_f32_e32 v218, v218
	v_rcp_f32_e32 v171, v171
	v_rcp_f32_e32 v173, v173
	v_rcp_f32_e32 v211, v211
	v_rcp_f32_e32 v219, v219
	s_nop 0
	v_pk_mul_f32 v[68:69], v[68:69], v[170:171]
	v_pk_mul_f32 v[70:71], v[70:71], v[172:173]
	v_pk_mul_f32 v[64:65], v[64:65], v[210:211]
	v_pk_mul_f32 v[66:67], v[66:67], v[218:219]
	v_cvt_pk_bf16_f32 v68, v68, v69
	v_cvt_pk_bf16_f32 v69, v70, v71
	v_cvt_pk_bf16_f32 v70, v64, v65
	v_cvt_pk_bf16_f32 v71, v66, v67
	global_store_dwordx4 v166, v[68:71], s[98:99] offset:256
	s_add_u32 s42, s18, 0x16000
	s_addc_u32 s43, s19, 0
	global_load_dwordx4 v[236:239], v216, s[42:43] offset:256
	s_waitcnt vmcnt(14)
	s_add_u32 s98, s48, 0x40000
	s_addc_u32 s99, s49, 0
	v_lshlrev_b32_e32 v170, 16, v132
	v_lshlrev_b32_e32 v172, 16, v133
	v_lshlrev_b32_e32 v210, 16, v134
	v_lshlrev_b32_e32 v218, 16, v135
	v_and_b32_e32 v171, 0xffff0000, v132
	v_and_b32_e32 v173, 0xffff0000, v133
	v_and_b32_e32 v211, 0xffff0000, v134
	v_and_b32_e32 v219, 0xffff0000, v135
	v_pk_mul_f32 v[170:171], v[170:171], s[60:61]
	v_pk_mul_f32 v[172:173], v[172:173], s[60:61]
	v_pk_mul_f32 v[210:211], v[210:211], s[60:61]
	v_pk_mul_f32 v[218:219], v[218:219], s[60:61]
	v_exp_f32_e32 v170, v170
	v_exp_f32_e32 v172, v172
	v_exp_f32_e32 v210, v210
	v_exp_f32_e32 v218, v218
	v_exp_f32_e32 v171, v171
	v_exp_f32_e32 v173, v173
	v_exp_f32_e32 v211, v211
	v_exp_f32_e32 v219, v219
	v_pk_add_f32 v[170:171], v[170:171], s[78:79]
	v_pk_add_f32 v[172:173], v[172:173], s[78:79]
	v_pk_add_f32 v[210:211], v[210:211], s[78:79]
	v_pk_add_f32 v[218:219], v[218:219], s[78:79]
	v_rcp_f32_e32 v170, v170
	v_rcp_f32_e32 v172, v172
	v_rcp_f32_e32 v210, v210
	v_rcp_f32_e32 v218, v218
	v_rcp_f32_e32 v171, v171
	v_rcp_f32_e32 v173, v173
	v_rcp_f32_e32 v211, v211
	v_rcp_f32_e32 v219, v219
	s_nop 0
	v_pk_mul_f32 v[60:61], v[60:61], v[170:171]
	v_pk_mul_f32 v[62:63], v[62:63], v[172:173]
	v_pk_mul_f32 v[56:57], v[56:57], v[210:211]
	v_pk_mul_f32 v[58:59], v[58:59], v[218:219]
	v_cvt_pk_bf16_f32 v60, v60, v61
	v_cvt_pk_bf16_f32 v61, v62, v63
	v_cvt_pk_bf16_f32 v62, v56, v57
	v_cvt_pk_bf16_f32 v63, v58, v59
	global_store_dwordx4 v166, v[60:63], s[98:99]
	s_waitcnt vmcnt(13)
	s_add_u32 s98, s48, 0x40000
	s_addc_u32 s99, s49, 0
	v_lshlrev_b32_e32 v170, 16, v136
	v_lshlrev_b32_e32 v172, 16, v137
	v_lshlrev_b32_e32 v210, 16, v138
	v_lshlrev_b32_e32 v218, 16, v139
	v_and_b32_e32 v171, 0xffff0000, v136
	v_and_b32_e32 v173, 0xffff0000, v137
	v_and_b32_e32 v211, 0xffff0000, v138
	v_and_b32_e32 v219, 0xffff0000, v139
	v_pk_mul_f32 v[170:171], v[170:171], s[60:61]
	v_pk_mul_f32 v[172:173], v[172:173], s[60:61]
	v_pk_mul_f32 v[210:211], v[210:211], s[60:61]
	v_pk_mul_f32 v[218:219], v[218:219], s[60:61]
	v_exp_f32_e32 v170, v170
	v_exp_f32_e32 v172, v172
	v_exp_f32_e32 v210, v210
	v_exp_f32_e32 v218, v218
	v_exp_f32_e32 v171, v171
	v_exp_f32_e32 v173, v173
	v_exp_f32_e32 v211, v211
	v_exp_f32_e32 v219, v219
	v_pk_add_f32 v[170:171], v[170:171], s[78:79]
	v_pk_add_f32 v[172:173], v[172:173], s[78:79]
	v_pk_add_f32 v[210:211], v[210:211], s[78:79]
	v_pk_add_f32 v[218:219], v[218:219], s[78:79]
	v_rcp_f32_e32 v170, v170
	v_rcp_f32_e32 v172, v172
	v_rcp_f32_e32 v210, v210
	v_rcp_f32_e32 v218, v218
	v_rcp_f32_e32 v171, v171
	v_rcp_f32_e32 v173, v173
	v_rcp_f32_e32 v211, v211
	v_rcp_f32_e32 v219, v219
	s_nop 0
	v_pk_mul_f32 v[52:53], v[52:53], v[170:171]
	v_pk_mul_f32 v[54:55], v[54:55], v[172:173]
	v_pk_mul_f32 v[48:49], v[48:49], v[210:211]
	v_pk_mul_f32 v[50:51], v[50:51], v[218:219]
	v_cvt_pk_bf16_f32 v52, v52, v53
	v_cvt_pk_bf16_f32 v53, v54, v55
	v_cvt_pk_bf16_f32 v54, v48, v49
	v_cvt_pk_bf16_f32 v55, v50, v51
	global_store_dwordx4 v166, v[52:55], s[98:99] offset:256
	s_waitcnt vmcnt(12)
	s_add_u32 s98, s48, 0x48000
	s_addc_u32 s99, s49, 0
	v_lshlrev_b32_e32 v170, 16, v140
	v_lshlrev_b32_e32 v172, 16, v141
	v_lshlrev_b32_e32 v210, 16, v142
	v_lshlrev_b32_e32 v218, 16, v143
	v_and_b32_e32 v171, 0xffff0000, v140
	v_and_b32_e32 v173, 0xffff0000, v141
	v_and_b32_e32 v211, 0xffff0000, v142
	v_and_b32_e32 v219, 0xffff0000, v143
	v_pk_mul_f32 v[170:171], v[170:171], s[60:61]
	v_pk_mul_f32 v[172:173], v[172:173], s[60:61]
	v_pk_mul_f32 v[210:211], v[210:211], s[60:61]
	v_pk_mul_f32 v[218:219], v[218:219], s[60:61]
	v_exp_f32_e32 v170, v170
	v_exp_f32_e32 v172, v172
	v_exp_f32_e32 v210, v210
	v_exp_f32_e32 v218, v218
	v_exp_f32_e32 v171, v171
	v_exp_f32_e32 v173, v173
	v_exp_f32_e32 v211, v211
	v_exp_f32_e32 v219, v219
	v_pk_add_f32 v[170:171], v[170:171], s[78:79]
	v_pk_add_f32 v[172:173], v[172:173], s[78:79]
	v_pk_add_f32 v[210:211], v[210:211], s[78:79]
	v_pk_add_f32 v[218:219], v[218:219], s[78:79]
	v_rcp_f32_e32 v170, v170
	v_rcp_f32_e32 v172, v172
	v_rcp_f32_e32 v210, v210
	v_rcp_f32_e32 v218, v218
	v_rcp_f32_e32 v171, v171
	v_rcp_f32_e32 v173, v173
	v_rcp_f32_e32 v211, v211
	v_rcp_f32_e32 v219, v219
	s_nop 0
	v_pk_mul_f32 v[44:45], v[44:45], v[170:171]
	v_pk_mul_f32 v[46:47], v[46:47], v[172:173]
	v_pk_mul_f32 v[40:41], v[40:41], v[210:211]
	v_pk_mul_f32 v[42:43], v[42:43], v[218:219]
	v_cvt_pk_bf16_f32 v44, v44, v45
	v_cvt_pk_bf16_f32 v45, v46, v47
	v_cvt_pk_bf16_f32 v46, v40, v41
	v_cvt_pk_bf16_f32 v47, v42, v43
	global_store_dwordx4 v166, v[44:47], s[98:99]
	s_waitcnt vmcnt(11)
	s_add_u32 s98, s48, 0x48000
	s_addc_u32 s99, s49, 0
	v_lshlrev_b32_e32 v170, 16, v144
	v_lshlrev_b32_e32 v172, 16, v145
	v_lshlrev_b32_e32 v210, 16, v146
	v_lshlrev_b32_e32 v218, 16, v147
	v_and_b32_e32 v171, 0xffff0000, v144
	v_and_b32_e32 v173, 0xffff0000, v145
	v_and_b32_e32 v211, 0xffff0000, v146
	v_and_b32_e32 v219, 0xffff0000, v147
	v_pk_mul_f32 v[170:171], v[170:171], s[60:61]
	v_pk_mul_f32 v[172:173], v[172:173], s[60:61]
	v_pk_mul_f32 v[210:211], v[210:211], s[60:61]
	v_pk_mul_f32 v[218:219], v[218:219], s[60:61]
	v_exp_f32_e32 v170, v170
	v_exp_f32_e32 v172, v172
	v_exp_f32_e32 v210, v210
	v_exp_f32_e32 v218, v218
	v_exp_f32_e32 v171, v171
	v_exp_f32_e32 v173, v173
	v_exp_f32_e32 v211, v211
	v_exp_f32_e32 v219, v219
	v_pk_add_f32 v[170:171], v[170:171], s[78:79]
	v_pk_add_f32 v[172:173], v[172:173], s[78:79]
	v_pk_add_f32 v[210:211], v[210:211], s[78:79]
	v_pk_add_f32 v[218:219], v[218:219], s[78:79]
	v_rcp_f32_e32 v170, v170
	v_rcp_f32_e32 v172, v172
	v_rcp_f32_e32 v210, v210
	v_rcp_f32_e32 v218, v218
	v_rcp_f32_e32 v171, v171
	v_rcp_f32_e32 v173, v173
	v_rcp_f32_e32 v211, v211
	v_rcp_f32_e32 v219, v219
	s_nop 0
	v_pk_mul_f32 v[36:37], v[36:37], v[170:171]
	v_pk_mul_f32 v[38:39], v[38:39], v[172:173]
	v_pk_mul_f32 v[32:33], v[32:33], v[210:211]
	v_pk_mul_f32 v[34:35], v[34:35], v[218:219]
	v_cvt_pk_bf16_f32 v36, v36, v37
	v_cvt_pk_bf16_f32 v37, v38, v39
	v_cvt_pk_bf16_f32 v38, v32, v33
	v_cvt_pk_bf16_f32 v39, v34, v35
	global_store_dwordx4 v166, v[36:39], s[98:99] offset:256
	s_waitcnt vmcnt(10)
	s_add_u32 s98, s48, 0x50000
	s_addc_u32 s99, s49, 0
	v_lshlrev_b32_e32 v170, 16, v224
	v_lshlrev_b32_e32 v172, 16, v225
	v_lshlrev_b32_e32 v210, 16, v226
	v_lshlrev_b32_e32 v218, 16, v227
	v_and_b32_e32 v171, 0xffff0000, v224
	v_and_b32_e32 v173, 0xffff0000, v225
	v_and_b32_e32 v211, 0xffff0000, v226
	v_and_b32_e32 v219, 0xffff0000, v227
	v_pk_mul_f32 v[170:171], v[170:171], s[60:61]
	v_pk_mul_f32 v[172:173], v[172:173], s[60:61]
	v_pk_mul_f32 v[210:211], v[210:211], s[60:61]
	v_pk_mul_f32 v[218:219], v[218:219], s[60:61]
	v_exp_f32_e32 v170, v170
	v_exp_f32_e32 v172, v172
	v_exp_f32_e32 v210, v210
	v_exp_f32_e32 v218, v218
	v_exp_f32_e32 v171, v171
	v_exp_f32_e32 v173, v173
	v_exp_f32_e32 v211, v211
	v_exp_f32_e32 v219, v219
	v_pk_add_f32 v[170:171], v[170:171], s[78:79]
	v_pk_add_f32 v[172:173], v[172:173], s[78:79]
	v_pk_add_f32 v[210:211], v[210:211], s[78:79]
	v_pk_add_f32 v[218:219], v[218:219], s[78:79]
	v_rcp_f32_e32 v170, v170
	v_rcp_f32_e32 v172, v172
	v_rcp_f32_e32 v210, v210
	v_rcp_f32_e32 v218, v218
	v_rcp_f32_e32 v171, v171
	v_rcp_f32_e32 v173, v173
	v_rcp_f32_e32 v211, v211
	v_rcp_f32_e32 v219, v219
	s_nop 0
	v_pk_mul_f32 v[28:29], v[28:29], v[170:171]
	v_pk_mul_f32 v[30:31], v[30:31], v[172:173]
	v_pk_mul_f32 v[24:25], v[24:25], v[210:211]
	v_pk_mul_f32 v[26:27], v[26:27], v[218:219]
	v_cvt_pk_bf16_f32 v28, v28, v29
	v_cvt_pk_bf16_f32 v29, v30, v31
	v_cvt_pk_bf16_f32 v30, v24, v25
	v_cvt_pk_bf16_f32 v31, v26, v27
	global_store_dwordx4 v166, v[28:31], s[98:99]
	s_waitcnt vmcnt(9)
	s_add_u32 s98, s48, 0x50000
	s_addc_u32 s99, s49, 0
	v_lshlrev_b32_e32 v170, 16, v228
	v_lshlrev_b32_e32 v172, 16, v229
	v_lshlrev_b32_e32 v210, 16, v230
	v_lshlrev_b32_e32 v218, 16, v231
	v_and_b32_e32 v171, 0xffff0000, v228
	v_and_b32_e32 v173, 0xffff0000, v229
	v_and_b32_e32 v211, 0xffff0000, v230
	v_and_b32_e32 v219, 0xffff0000, v231
	v_pk_mul_f32 v[170:171], v[170:171], s[60:61]
	v_pk_mul_f32 v[172:173], v[172:173], s[60:61]
	v_pk_mul_f32 v[210:211], v[210:211], s[60:61]
	v_pk_mul_f32 v[218:219], v[218:219], s[60:61]
	v_exp_f32_e32 v170, v170
	v_exp_f32_e32 v172, v172
	v_exp_f32_e32 v210, v210
	v_exp_f32_e32 v218, v218
	v_exp_f32_e32 v171, v171
	v_exp_f32_e32 v173, v173
	v_exp_f32_e32 v211, v211
	v_exp_f32_e32 v219, v219
	v_pk_add_f32 v[170:171], v[170:171], s[78:79]
	v_pk_add_f32 v[172:173], v[172:173], s[78:79]
	v_pk_add_f32 v[210:211], v[210:211], s[78:79]
	v_pk_add_f32 v[218:219], v[218:219], s[78:79]
	v_rcp_f32_e32 v170, v170
	v_rcp_f32_e32 v172, v172
	v_rcp_f32_e32 v210, v210
	v_rcp_f32_e32 v218, v218
	v_rcp_f32_e32 v171, v171
	v_rcp_f32_e32 v173, v173
	v_rcp_f32_e32 v211, v211
	v_rcp_f32_e32 v219, v219
	s_nop 0
	v_pk_mul_f32 v[20:21], v[20:21], v[170:171]
	v_pk_mul_f32 v[22:23], v[22:23], v[172:173]
	v_pk_mul_f32 v[16:17], v[16:17], v[210:211]
	v_pk_mul_f32 v[18:19], v[18:19], v[218:219]
	v_cvt_pk_bf16_f32 v20, v20, v21
	v_cvt_pk_bf16_f32 v21, v22, v23
	v_cvt_pk_bf16_f32 v22, v16, v17
	v_cvt_pk_bf16_f32 v23, v18, v19
	global_store_dwordx4 v166, v[20:23], s[98:99] offset:256
	s_waitcnt vmcnt(8)
	s_add_u32 s98, s48, 0x58000
	s_addc_u32 s99, s49, 0
	v_lshlrev_b32_e32 v170, 16, v232
	v_lshlrev_b32_e32 v172, 16, v233
	v_lshlrev_b32_e32 v210, 16, v234
	v_lshlrev_b32_e32 v218, 16, v235
	v_and_b32_e32 v171, 0xffff0000, v232
	v_and_b32_e32 v173, 0xffff0000, v233
	v_and_b32_e32 v211, 0xffff0000, v234
	v_and_b32_e32 v219, 0xffff0000, v235
	v_pk_mul_f32 v[170:171], v[170:171], s[60:61]
	v_pk_mul_f32 v[172:173], v[172:173], s[60:61]
	v_pk_mul_f32 v[210:211], v[210:211], s[60:61]
	v_pk_mul_f32 v[218:219], v[218:219], s[60:61]
	v_exp_f32_e32 v170, v170
	v_exp_f32_e32 v172, v172
	v_exp_f32_e32 v210, v210
	v_exp_f32_e32 v218, v218
	v_exp_f32_e32 v171, v171
	v_exp_f32_e32 v173, v173
	v_exp_f32_e32 v211, v211
	v_exp_f32_e32 v219, v219
	v_pk_add_f32 v[170:171], v[170:171], s[78:79]
	v_pk_add_f32 v[172:173], v[172:173], s[78:79]
	v_pk_add_f32 v[210:211], v[210:211], s[78:79]
	v_pk_add_f32 v[218:219], v[218:219], s[78:79]
	v_rcp_f32_e32 v170, v170
	v_rcp_f32_e32 v172, v172
	v_rcp_f32_e32 v210, v210
	v_rcp_f32_e32 v218, v218
	v_rcp_f32_e32 v171, v171
	v_rcp_f32_e32 v173, v173
	v_rcp_f32_e32 v211, v211
	v_rcp_f32_e32 v219, v219
	s_nop 0
	v_pk_mul_f32 v[12:13], v[12:13], v[170:171]
	v_pk_mul_f32 v[14:15], v[14:15], v[172:173]
	v_pk_mul_f32 v[8:9], v[8:9], v[210:211]
	v_pk_mul_f32 v[10:11], v[10:11], v[218:219]
	v_cvt_pk_bf16_f32 v12, v12, v13
	v_cvt_pk_bf16_f32 v13, v14, v15
	v_cvt_pk_bf16_f32 v14, v8, v9
	v_cvt_pk_bf16_f32 v15, v10, v11
	global_store_dwordx4 v166, v[12:15], s[98:99]
	s_waitcnt vmcnt(7)
	s_add_u32 s98, s48, 0x58000
	s_addc_u32 s99, s49, 0
	v_lshlrev_b32_e32 v170, 16, v236
	v_lshlrev_b32_e32 v172, 16, v237
	v_lshlrev_b32_e32 v210, 16, v238
	v_lshlrev_b32_e32 v218, 16, v239
	v_and_b32_e32 v171, 0xffff0000, v236
	v_and_b32_e32 v173, 0xffff0000, v237
	v_and_b32_e32 v211, 0xffff0000, v238
	v_and_b32_e32 v219, 0xffff0000, v239
	v_pk_mul_f32 v[170:171], v[170:171], s[60:61]
	v_pk_mul_f32 v[172:173], v[172:173], s[60:61]
	v_pk_mul_f32 v[210:211], v[210:211], s[60:61]
	v_pk_mul_f32 v[218:219], v[218:219], s[60:61]
	v_exp_f32_e32 v170, v170
	v_exp_f32_e32 v172, v172
	v_exp_f32_e32 v210, v210
	v_exp_f32_e32 v218, v218
	v_exp_f32_e32 v171, v171
	v_exp_f32_e32 v173, v173
	v_exp_f32_e32 v211, v211
	v_exp_f32_e32 v219, v219
	v_pk_add_f32 v[170:171], v[170:171], s[78:79]
	v_pk_add_f32 v[172:173], v[172:173], s[78:79]
	v_pk_add_f32 v[210:211], v[210:211], s[78:79]
	v_pk_add_f32 v[218:219], v[218:219], s[78:79]
	v_rcp_f32_e32 v170, v170
	v_rcp_f32_e32 v172, v172
	v_rcp_f32_e32 v210, v210
	v_rcp_f32_e32 v218, v218
	v_rcp_f32_e32 v171, v171
	v_rcp_f32_e32 v173, v173
	v_rcp_f32_e32 v211, v211
	v_rcp_f32_e32 v219, v219
	s_nop 0
	v_pk_mul_f32 v[4:5], v[4:5], v[170:171]
	v_pk_mul_f32 v[6:7], v[6:7], v[172:173]
	v_pk_mul_f32 v[0:1], v[0:1], v[210:211]
	v_pk_mul_f32 v[2:3], v[2:3], v[218:219]
	v_cvt_pk_bf16_f32 v4, v4, v5
	v_cvt_pk_bf16_f32 v5, v6, v7
	v_cvt_pk_bf16_f32 v6, v0, v1
	v_cvt_pk_bf16_f32 v7, v2, v3
	global_store_dwordx4 v166, v[4:7], s[98:99] offset:256
	s_branch .Lp6e2_done
	s_mul_i32 s18, s43, 49
	s_add_i32 s18, s42, s18
	v_lshl_or_b32 v132, s42, 8, v197
	s_add_i32 s18, s18, 45
	v_lshl_add_u32 v186, s43, 8, v169
	s_ashr_i32 s19, s18, 31
	v_ashrrev_i32_e32 v133, 31, v132
	s_lshl_b64 s[18:19], s[18:19], 17
	v_lshlrev_b64 v[170:171], 1, v[132:133]
	v_lshlrev_b32_e32 v132, 9, v186
	v_lshl_add_u64 v[188:189], v[178:179], 0, s[18:19]
	v_ashrrev_i32_e32 v187, 31, v186
	v_and_b32_e32 v166, 0x19e00, v132
	v_lshl_add_u64 v[190:191], v[176:177], 0, v[170:171]
	v_lshl_add_u64 v[132:133], v[188:189], 0, v[166:167]
	v_lshlrev_b64 v[172:173], 11, v[186:187]
	v_lshl_add_u64 v[134:135], v[190:191], 0, v[172:173]
	global_load_dwordx4 v[200:203], v[132:133], off
	global_load_dwordx4 v[152:155], v[132:133], off offset:256
	global_load_dwordx4 v[204:207], v[134:135], off
	global_load_dwordx4 v[148:151], v[134:135], off offset:256
	v_or_b32_e32 v132, 16, v186
	v_ashrrev_i32_e32 v133, 31, v132
	v_lshlrev_b32_e32 v134, 9, v132
	v_and_b32_e32 v166, 0x1fe00, v134
	v_lshlrev_b64 v[192:193], 11, v[132:133]
	v_lshl_add_u64 v[134:135], v[188:189], 0, v[166:167]
	v_lshl_add_u64 v[132:133], v[190:191], 0, v[192:193]
	global_load_dwordx4 v[144:147], v[134:135], off
	global_load_dwordx4 v[136:139], v[134:135], off offset:256
	global_load_dwordx4 v[140:143], v[132:133], off
	s_nop 0
	global_load_dwordx4 v[132:135], v[132:133], off offset:256
	v_lshl_add_u64 v[184:185], v[164:165], 0, v[170:171]
	s_waitcnt vmcnt(0)
	v_lshlrev_b32_e32 v166, 16, v200
	v_mul_f32_e32 v166, 0xbfb8aa3b, v166
	v_exp_f32_e32 v166, v166
	v_lshl_add_u64 v[194:195], v[184:185], 0, v[172:173]
	v_lshlrev_b32_e32 v172, 16, v204
	v_and_b32_e32 v173, 0xffff0000, v204
	v_add_f32_e32 v166, 1.0, v166
	v_rcp_f32_e32 v170, v166
	v_and_b32_e32 v166, 0xffff0000, v200
	v_mul_f32_e32 v166, 0xbfb8aa3b, v166
	v_exp_f32_e32 v166, v166
	s_nop 0
	v_add_f32_e32 v166, 1.0, v166
	v_rcp_f32_e32 v171, v166
	v_lshlrev_b32_e32 v166, 16, v201
	v_mul_f32_e32 v166, 0xbfb8aa3b, v166
	v_exp_f32_e32 v166, v166
	v_pk_fma_f32 v[128:129], v[128:129], v[170:171], v[172:173]
	v_lshlrev_b32_e32 v172, 16, v205
	v_and_b32_e32 v173, 0xffff0000, v205
	v_add_f32_e32 v166, 1.0, v166
	v_rcp_f32_e32 v170, v166
	v_and_b32_e32 v166, 0xffff0000, v201
	v_mul_f32_e32 v166, 0xbfb8aa3b, v166
	v_exp_f32_e32 v166, v166
	s_nop 0
	v_add_f32_e32 v166, 1.0, v166
	v_rcp_f32_e32 v171, v166
	v_lshlrev_b32_e32 v166, 16, v202
	v_mul_f32_e32 v166, 0xbfb8aa3b, v166
	v_exp_f32_e32 v166, v166
	v_pk_fma_f32 v[130:131], v[130:131], v[170:171], v[172:173]
	v_lshlrev_b32_e32 v172, 16, v206
	v_and_b32_e32 v173, 0xffff0000, v206
	v_add_f32_e32 v166, 1.0, v166
	v_rcp_f32_e32 v170, v166
	v_and_b32_e32 v166, 0xffff0000, v202
	v_mul_f32_e32 v166, 0xbfb8aa3b, v166
	v_exp_f32_e32 v166, v166
	s_nop 0
	v_add_f32_e32 v166, 1.0, v166
	v_rcp_f32_e32 v171, v166
	s_nop 0
	v_pk_fma_f32 v[170:171], v[124:125], v[170:171], v[172:173]
	v_lshlrev_b32_e32 v124, 16, v203
	v_and_b32_e32 v125, 0xffff0000, v203
	v_mul_f32_e32 v124, 0xbfb8aa3b, v124
	v_mul_f32_e32 v125, 0xbfb8aa3b, v125
	v_exp_f32_e32 v124, v124
	v_exp_f32_e32 v125, v125
	v_lshlrev_b32_e32 v172, 16, v207
	v_and_b32_e32 v173, 0xffff0000, v207
	v_add_f32_e32 v124, 1.0, v124
	v_add_f32_e32 v125, 1.0, v125
	v_rcp_f32_e32 v124, v124
	v_rcp_f32_e32 v125, v125
	s_nop 0
	v_pk_fma_f32 v[172:173], v[126:127], v[124:125], v[172:173]
	v_cvt_pk_bf16_f32 v124, v128, v129
	v_cvt_pk_bf16_f32 v125, v130, v131
	v_cvt_pk_bf16_f32 v126, v170, v171
	v_cvt_pk_bf16_f32 v127, v172, v173
	global_store_dwordx4 v[194:195], v[124:127], off
	s_nop 1
	v_lshlrev_b32_e32 v124, 16, v152
	v_and_b32_e32 v125, 0xffff0000, v152
	v_mul_f32_e32 v124, 0xbfb8aa3b, v124
	v_mul_f32_e32 v125, 0xbfb8aa3b, v125
	v_exp_f32_e32 v124, v124
	v_exp_f32_e32 v125, v125
	v_lshlrev_b32_e32 v126, 16, v148
	v_and_b32_e32 v127, 0xffff0000, v148
	v_add_f32_e32 v124, 1.0, v124
	v_add_f32_e32 v125, 1.0, v125
	v_rcp_f32_e32 v124, v124
	v_rcp_f32_e32 v125, v125
	s_nop 0
	v_pk_fma_f32 v[120:121], v[120:121], v[124:125], v[126:127]
	v_lshlrev_b32_e32 v124, 16, v153
	v_and_b32_e32 v125, 0xffff0000, v153
	v_mul_f32_e32 v124, 0xbfb8aa3b, v124
	v_mul_f32_e32 v125, 0xbfb8aa3b, v125
	v_exp_f32_e32 v124, v124
	v_exp_f32_e32 v125, v125
	v_lshlrev_b32_e32 v126, 16, v149
	v_and_b32_e32 v127, 0xffff0000, v149
	v_add_f32_e32 v124, 1.0, v124
	v_add_f32_e32 v125, 1.0, v125
	v_rcp_f32_e32 v124, v124
	v_rcp_f32_e32 v125, v125
	s_nop 0
	v_pk_fma_f32 v[122:123], v[122:123], v[124:125], v[126:127]
	v_lshlrev_b32_e32 v124, 16, v154
	v_and_b32_e32 v125, 0xffff0000, v154
	v_mul_f32_e32 v124, 0xbfb8aa3b, v124
	v_mul_f32_e32 v125, 0xbfb8aa3b, v125
	v_exp_f32_e32 v124, v124
	v_exp_f32_e32 v125, v125
	v_lshlrev_b32_e32 v126, 16, v150
	v_and_b32_e32 v127, 0xffff0000, v150
	v_add_f32_e32 v124, 1.0, v124
	v_add_f32_e32 v125, 1.0, v125
	v_rcp_f32_e32 v124, v124
	v_rcp_f32_e32 v125, v125
	s_nop 0
	v_pk_fma_f32 v[124:125], v[116:117], v[124:125], v[126:127]
	v_lshlrev_b32_e32 v116, 16, v155
	v_and_b32_e32 v117, 0xffff0000, v155
	v_mul_f32_e32 v116, 0xbfb8aa3b, v116
	v_mul_f32_e32 v117, 0xbfb8aa3b, v117
	v_exp_f32_e32 v116, v116
	v_exp_f32_e32 v117, v117
	v_lshlrev_b32_e32 v126, 16, v151
	v_and_b32_e32 v127, 0xffff0000, v151
	v_add_f32_e32 v116, 1.0, v116
	v_add_f32_e32 v117, 1.0, v117
	v_rcp_f32_e32 v116, v116
	v_rcp_f32_e32 v117, v117
	s_nop 0
	v_pk_fma_f32 v[126:127], v[118:119], v[116:117], v[126:127]
	v_cvt_pk_bf16_f32 v116, v120, v121
	v_cvt_pk_bf16_f32 v117, v122, v123
	v_cvt_pk_bf16_f32 v118, v124, v125
	v_cvt_pk_bf16_f32 v119, v126, v127
	global_store_dwordx4 v[194:195], v[116:119], off offset:256
	v_lshlrev_b32_e32 v120, 16, v140
	v_and_b32_e32 v121, 0xffff0000, v140
	v_lshlrev_b32_e32 v118, 16, v144
	v_and_b32_e32 v119, 0xffff0000, v144
	v_mul_f32_e32 v118, 0xbfb8aa3b, v118
	v_mul_f32_e32 v119, 0xbfb8aa3b, v119
	v_exp_f32_e32 v118, v118
	v_exp_f32_e32 v119, v119
	v_lshl_add_u64 v[116:117], v[184:185], 0, v[192:193]
	v_add_f32_e32 v118, 1.0, v118
	v_add_f32_e32 v119, 1.0, v119
	v_rcp_f32_e32 v118, v118
	v_rcp_f32_e32 v119, v119
	s_nop 0
	v_pk_fma_f32 v[112:113], v[112:113], v[118:119], v[120:121]
	v_lshlrev_b32_e32 v118, 16, v145
	v_and_b32_e32 v119, 0xffff0000, v145
	v_mul_f32_e32 v118, 0xbfb8aa3b, v118
	v_mul_f32_e32 v119, 0xbfb8aa3b, v119
	v_exp_f32_e32 v118, v118
	v_exp_f32_e32 v119, v119
	v_lshlrev_b32_e32 v120, 16, v141
	v_and_b32_e32 v121, 0xffff0000, v141
	v_add_f32_e32 v118, 1.0, v118
	v_add_f32_e32 v119, 1.0, v119
	v_rcp_f32_e32 v118, v118
	v_rcp_f32_e32 v119, v119
	s_nop 0
	v_pk_fma_f32 v[114:115], v[114:115], v[118:119], v[120:121]
	v_lshlrev_b32_e32 v118, 16, v146
	v_and_b32_e32 v119, 0xffff0000, v146
	v_mul_f32_e32 v118, 0xbfb8aa3b, v118
	v_mul_f32_e32 v119, 0xbfb8aa3b, v119
	v_exp_f32_e32 v118, v118
	v_exp_f32_e32 v119, v119
	v_lshlrev_b32_e32 v120, 16, v142
	v_and_b32_e32 v121, 0xffff0000, v142
	v_add_f32_e32 v118, 1.0, v118
	v_add_f32_e32 v119, 1.0, v119
	v_rcp_f32_e32 v118, v118
	v_rcp_f32_e32 v119, v119
	s_nop 0
	v_pk_fma_f32 v[118:119], v[108:109], v[118:119], v[120:121]
	v_lshlrev_b32_e32 v108, 16, v147
	v_and_b32_e32 v109, 0xffff0000, v147
	v_mul_f32_e32 v108, 0xbfb8aa3b, v108
	v_mul_f32_e32 v109, 0xbfb8aa3b, v109
	v_exp_f32_e32 v108, v108
	v_exp_f32_e32 v109, v109
	v_lshlrev_b32_e32 v120, 16, v143
	v_and_b32_e32 v121, 0xffff0000, v143
	v_add_f32_e32 v108, 1.0, v108
	v_add_f32_e32 v109, 1.0, v109
	v_rcp_f32_e32 v108, v108
	v_rcp_f32_e32 v109, v109
	s_nop 0
	v_pk_fma_f32 v[120:121], v[110:111], v[108:109], v[120:121]
	v_cvt_pk_bf16_f32 v108, v112, v113
	v_cvt_pk_bf16_f32 v109, v114, v115
	v_cvt_pk_bf16_f32 v110, v118, v119
	v_cvt_pk_bf16_f32 v111, v120, v121
	global_store_dwordx4 v[116:117], v[108:111], off
	s_nop 1
	v_lshlrev_b32_e32 v108, 16, v136
	v_and_b32_e32 v109, 0xffff0000, v136
	v_mul_f32_e32 v108, 0xbfb8aa3b, v108
	v_mul_f32_e32 v109, 0xbfb8aa3b, v109
	v_exp_f32_e32 v108, v108
	v_exp_f32_e32 v109, v109
	v_lshlrev_b32_e32 v110, 16, v132
	v_and_b32_e32 v111, 0xffff0000, v132
	v_add_f32_e32 v108, 1.0, v108
	v_add_f32_e32 v109, 1.0, v109
	v_rcp_f32_e32 v108, v108
	v_rcp_f32_e32 v109, v109
	s_nop 0
	v_pk_fma_f32 v[104:105], v[104:105], v[108:109], v[110:111]
	v_lshlrev_b32_e32 v108, 16, v137
	v_and_b32_e32 v109, 0xffff0000, v137
	v_mul_f32_e32 v108, 0xbfb8aa3b, v108
	v_mul_f32_e32 v109, 0xbfb8aa3b, v109
	v_exp_f32_e32 v108, v108
	v_exp_f32_e32 v109, v109
	v_lshlrev_b32_e32 v110, 16, v133
	v_and_b32_e32 v111, 0xffff0000, v133
	v_add_f32_e32 v108, 1.0, v108
	v_add_f32_e32 v109, 1.0, v109
	v_rcp_f32_e32 v108, v108
	v_rcp_f32_e32 v109, v109
	s_nop 0
	v_pk_fma_f32 v[106:107], v[106:107], v[108:109], v[110:111]
	v_lshlrev_b32_e32 v108, 16, v138
	v_and_b32_e32 v109, 0xffff0000, v138
	v_mul_f32_e32 v108, 0xbfb8aa3b, v108
	v_mul_f32_e32 v109, 0xbfb8aa3b, v109
	v_exp_f32_e32 v108, v108
	v_exp_f32_e32 v109, v109
	v_lshlrev_b32_e32 v110, 16, v134
	v_and_b32_e32 v111, 0xffff0000, v134
	v_add_f32_e32 v108, 1.0, v108
	v_add_f32_e32 v109, 1.0, v109
	v_rcp_f32_e32 v108, v108
	v_rcp_f32_e32 v109, v109
	s_nop 0
	v_pk_fma_f32 v[108:109], v[100:101], v[108:109], v[110:111]
	v_lshlrev_b32_e32 v100, 16, v139
	v_and_b32_e32 v101, 0xffff0000, v139
	v_mul_f32_e32 v100, 0xbfb8aa3b, v100
	v_mul_f32_e32 v101, 0xbfb8aa3b, v101
	v_exp_f32_e32 v100, v100
	v_exp_f32_e32 v101, v101
	v_lshlrev_b32_e32 v110, 16, v135
	v_and_b32_e32 v111, 0xffff0000, v135
	v_add_f32_e32 v100, 1.0, v100
	v_add_f32_e32 v101, 1.0, v101
	v_rcp_f32_e32 v100, v100
	v_rcp_f32_e32 v101, v101
	s_nop 0
	v_pk_fma_f32 v[110:111], v[102:103], v[100:101], v[110:111]
	v_cvt_pk_bf16_f32 v100, v104, v105
	v_cvt_pk_bf16_f32 v101, v106, v107
	v_cvt_pk_bf16_f32 v102, v108, v109
	v_cvt_pk_bf16_f32 v103, v110, v111
	global_store_dwordx4 v[116:117], v[100:103], off offset:256
	s_nop 1
	v_or_b32_e32 v100, 32, v186
	v_ashrrev_i32_e32 v101, 31, v100
	v_lshlrev_b32_e32 v102, 9, v100
	v_and_b32_e32 v166, 0x1fe00, v102
	v_lshlrev_b64 v[126:127], 11, v[100:101]
	v_lshl_add_u64 v[102:103], v[188:189], 0, v[166:167]
	v_lshl_add_u64 v[100:101], v[190:191], 0, v[126:127]
	global_load_dwordx4 v[128:131], v[102:103], off
	global_load_dwordx4 v[120:123], v[102:103], off offset:256
	global_load_dwordx4 v[132:135], v[100:101], off
	global_load_dwordx4 v[116:119], v[100:101], off offset:256
	v_or_b32_e32 v100, 48, v186
	v_ashrrev_i32_e32 v101, 31, v100
	v_lshlrev_b32_e32 v102, 9, v100
	v_and_b32_e32 v166, 0x1fe00, v102
	v_lshlrev_b64 v[124:125], 11, v[100:101]
	v_lshl_add_u64 v[102:103], v[188:189], 0, v[166:167]
	v_lshl_add_u64 v[100:101], v[190:191], 0, v[124:125]
	global_load_dwordx4 v[112:115], v[102:103], off
	global_load_dwordx4 v[104:107], v[102:103], off offset:256
	global_load_dwordx4 v[108:111], v[100:101], off
	s_nop 0
	global_load_dwordx4 v[100:103], v[100:101], off offset:256
	s_waitcnt vmcnt(0)
	v_lshlrev_b32_e32 v136, 16, v128
	v_and_b32_e32 v128, 0xffff0000, v128
	v_mul_f32_e32 v128, 0xbfb8aa3b, v128
	v_exp_f32_e32 v128, v128
	v_lshlrev_b32_e32 v138, 16, v132
	v_and_b32_e32 v139, 0xffff0000, v132
	v_lshlrev_b32_e32 v132, 16, v133
	v_add_f32_e32 v128, 1.0, v128
	v_rcp_f32_e32 v137, v128
	v_lshlrev_b32_e32 v128, 16, v129
	v_and_b32_e32 v129, 0xffff0000, v129
	v_mul_f32_e32 v128, 0xbfb8aa3b, v128
	v_mul_f32_e32 v129, 0xbfb8aa3b, v129
	v_exp_f32_e32 v128, v128
	v_exp_f32_e32 v129, v129
	v_and_b32_e32 v133, 0xffff0000, v133
	v_mul_f32_e32 v136, 0xbfb8aa3b, v136
	v_add_f32_e32 v128, 1.0, v128
	v_add_f32_e32 v129, 1.0, v129
	v_rcp_f32_e32 v128, v128
	v_rcp_f32_e32 v129, v129
	v_exp_f32_e32 v136, v136
	v_lshl_add_u64 v[126:127], v[184:185], 0, v[126:127]
	v_pk_fma_f32 v[98:99], v[98:99], v[128:129], v[132:133]
	v_lshlrev_b32_e32 v128, 16, v130
	v_and_b32_e32 v129, 0xffff0000, v130
	v_mul_f32_e32 v128, 0xbfb8aa3b, v128
	v_mul_f32_e32 v129, 0xbfb8aa3b, v129
	v_exp_f32_e32 v128, v128
	v_exp_f32_e32 v129, v129
	v_lshlrev_b32_e32 v132, 16, v134
	v_and_b32_e32 v133, 0xffff0000, v134
	v_add_f32_e32 v128, 1.0, v128
	v_add_f32_e32 v129, 1.0, v129
	v_rcp_f32_e32 v128, v128
	v_rcp_f32_e32 v129, v129
	v_add_f32_e32 v136, 1.0, v136
	v_rcp_f32_e32 v136, v136
	v_lshlrev_b32_e32 v130, 16, v135
	v_pk_fma_f32 v[128:129], v[92:93], v[128:129], v[132:133]
	v_lshlrev_b32_e32 v92, 16, v131
	v_and_b32_e32 v93, 0xffff0000, v131
	v_mul_f32_e32 v92, 0xbfb8aa3b, v92
	v_mul_f32_e32 v93, 0xbfb8aa3b, v93
	v_exp_f32_e32 v92, v92
	v_exp_f32_e32 v93, v93
	v_and_b32_e32 v131, 0xffff0000, v135
	v_pk_fma_f32 v[96:97], v[96:97], v[136:137], v[138:139]
	v_add_f32_e32 v92, 1.0, v92
	v_add_f32_e32 v93, 1.0, v93
	v_rcp_f32_e32 v92, v92
	v_rcp_f32_e32 v93, v93
	s_nop 0
	v_pk_fma_f32 v[130:131], v[94:95], v[92:93], v[130:131]
	v_cvt_pk_bf16_f32 v92, v96, v97
	v_cvt_pk_bf16_f32 v93, v98, v99
	v_cvt_pk_bf16_f32 v94, v128, v129
	v_cvt_pk_bf16_f32 v95, v130, v131
	global_store_dwordx4 v[126:127], v[92:95], off
	s_nop 1
	v_lshlrev_b32_e32 v92, 16, v120
	v_and_b32_e32 v93, 0xffff0000, v120
	v_mul_f32_e32 v92, 0xbfb8aa3b, v92
	v_mul_f32_e32 v93, 0xbfb8aa3b, v93
	v_exp_f32_e32 v92, v92
	v_exp_f32_e32 v93, v93
	v_lshlrev_b32_e32 v94, 16, v116
	v_and_b32_e32 v95, 0xffff0000, v116
	v_add_f32_e32 v92, 1.0, v92
	v_add_f32_e32 v93, 1.0, v93
	v_rcp_f32_e32 v92, v92
	v_rcp_f32_e32 v93, v93
	s_nop 0
	v_pk_fma_f32 v[88:89], v[88:89], v[92:93], v[94:95]
	v_lshlrev_b32_e32 v92, 16, v121
	v_and_b32_e32 v93, 0xffff0000, v121
	v_mul_f32_e32 v92, 0xbfb8aa3b, v92
	v_mul_f32_e32 v93, 0xbfb8aa3b, v93
	v_exp_f32_e32 v92, v92
	v_exp_f32_e32 v93, v93
	v_lshlrev_b32_e32 v94, 16, v117
	v_and_b32_e32 v95, 0xffff0000, v117
	v_add_f32_e32 v92, 1.0, v92
	v_add_f32_e32 v93, 1.0, v93
	v_rcp_f32_e32 v92, v92
	v_rcp_f32_e32 v93, v93
	s_nop 0
	v_pk_fma_f32 v[90:91], v[90:91], v[92:93], v[94:95]
	v_lshlrev_b32_e32 v92, 16, v122
	v_and_b32_e32 v93, 0xffff0000, v122
	v_mul_f32_e32 v92, 0xbfb8aa3b, v92
	v_mul_f32_e32 v93, 0xbfb8aa3b, v93
	v_exp_f32_e32 v92, v92
	v_exp_f32_e32 v93, v93
	v_lshlrev_b32_e32 v94, 16, v118
	v_and_b32_e32 v95, 0xffff0000, v118
	v_add_f32_e32 v92, 1.0, v92
	v_add_f32_e32 v93, 1.0, v93
	v_rcp_f32_e32 v92, v92
	v_rcp_f32_e32 v93, v93
	s_nop 0
	v_pk_fma_f32 v[92:93], v[84:85], v[92:93], v[94:95]
	v_lshlrev_b32_e32 v84, 16, v123
	v_and_b32_e32 v85, 0xffff0000, v123
	v_mul_f32_e32 v84, 0xbfb8aa3b, v84
	v_mul_f32_e32 v85, 0xbfb8aa3b, v85
	v_exp_f32_e32 v84, v84
	v_exp_f32_e32 v85, v85
	v_lshlrev_b32_e32 v94, 16, v119
	v_and_b32_e32 v95, 0xffff0000, v119
	v_add_f32_e32 v84, 1.0, v84
	v_add_f32_e32 v85, 1.0, v85
	v_rcp_f32_e32 v84, v84
	v_rcp_f32_e32 v85, v85
	s_nop 0
	v_pk_fma_f32 v[94:95], v[86:87], v[84:85], v[94:95]
	v_cvt_pk_bf16_f32 v84, v88, v89
	v_cvt_pk_bf16_f32 v85, v90, v91
	v_cvt_pk_bf16_f32 v86, v92, v93
	v_cvt_pk_bf16_f32 v87, v94, v95
	global_store_dwordx4 v[126:127], v[84:87], off offset:256
	v_lshlrev_b32_e32 v88, 16, v108
	v_and_b32_e32 v89, 0xffff0000, v108
	v_lshlrev_b32_e32 v86, 16, v112
	v_and_b32_e32 v87, 0xffff0000, v112
	v_mul_f32_e32 v86, 0xbfb8aa3b, v86
	v_mul_f32_e32 v87, 0xbfb8aa3b, v87
	v_exp_f32_e32 v86, v86
	v_exp_f32_e32 v87, v87
	v_lshl_add_u64 v[84:85], v[184:185], 0, v[124:125]
	v_add_f32_e32 v86, 1.0, v86
	v_add_f32_e32 v87, 1.0, v87
	v_rcp_f32_e32 v86, v86
	v_rcp_f32_e32 v87, v87
	s_nop 0
	v_pk_fma_f32 v[76:77], v[76:77], v[86:87], v[88:89]
	v_lshlrev_b32_e32 v86, 16, v113
	v_and_b32_e32 v87, 0xffff0000, v113
	v_mul_f32_e32 v86, 0xbfb8aa3b, v86
	v_mul_f32_e32 v87, 0xbfb8aa3b, v87
	v_exp_f32_e32 v86, v86
	v_exp_f32_e32 v87, v87
	v_lshlrev_b32_e32 v88, 16, v109
	v_and_b32_e32 v89, 0xffff0000, v109
	v_add_f32_e32 v86, 1.0, v86
	v_add_f32_e32 v87, 1.0, v87
	v_rcp_f32_e32 v86, v86
	v_rcp_f32_e32 v87, v87
	s_nop 0
	v_pk_fma_f32 v[78:79], v[78:79], v[86:87], v[88:89]
	v_lshlrev_b32_e32 v86, 16, v114
	v_and_b32_e32 v87, 0xffff0000, v114
	v_mul_f32_e32 v86, 0xbfb8aa3b, v86
	v_mul_f32_e32 v87, 0xbfb8aa3b, v87
	v_exp_f32_e32 v86, v86
	v_exp_f32_e32 v87, v87
	v_lshlrev_b32_e32 v88, 16, v110
	v_and_b32_e32 v89, 0xffff0000, v110
	v_add_f32_e32 v86, 1.0, v86
	v_add_f32_e32 v87, 1.0, v87
	v_rcp_f32_e32 v86, v86
	v_rcp_f32_e32 v87, v87
	s_nop 0
	v_pk_fma_f32 v[86:87], v[72:73], v[86:87], v[88:89]
	v_lshlrev_b32_e32 v72, 16, v115
	v_and_b32_e32 v73, 0xffff0000, v115
	v_mul_f32_e32 v72, 0xbfb8aa3b, v72
	v_mul_f32_e32 v73, 0xbfb8aa3b, v73
	v_exp_f32_e32 v72, v72
	v_exp_f32_e32 v73, v73
	v_lshlrev_b32_e32 v88, 16, v111
	v_and_b32_e32 v89, 0xffff0000, v111
	v_add_f32_e32 v72, 1.0, v72
	v_add_f32_e32 v73, 1.0, v73
	v_rcp_f32_e32 v72, v72
	v_rcp_f32_e32 v73, v73
	s_nop 0
	v_pk_fma_f32 v[88:89], v[74:75], v[72:73], v[88:89]
	v_cvt_pk_bf16_f32 v72, v76, v77
	v_cvt_pk_bf16_f32 v73, v78, v79
	v_cvt_pk_bf16_f32 v74, v86, v87
	v_cvt_pk_bf16_f32 v75, v88, v89
	global_store_dwordx4 v[84:85], v[72:75], off
	s_nop 1
	v_lshlrev_b32_e32 v72, 16, v104
	v_and_b32_e32 v73, 0xffff0000, v104
	v_mul_f32_e32 v72, 0xbfb8aa3b, v72
	v_mul_f32_e32 v73, 0xbfb8aa3b, v73
	v_exp_f32_e32 v72, v72
	v_exp_f32_e32 v73, v73
	v_lshlrev_b32_e32 v74, 16, v100
	v_and_b32_e32 v75, 0xffff0000, v100
	v_add_f32_e32 v72, 1.0, v72
	v_add_f32_e32 v73, 1.0, v73
	v_rcp_f32_e32 v72, v72
	v_rcp_f32_e32 v73, v73
	s_nop 0
	v_pk_fma_f32 v[68:69], v[68:69], v[72:73], v[74:75]
	v_lshlrev_b32_e32 v72, 16, v105
	v_and_b32_e32 v73, 0xffff0000, v105
	v_mul_f32_e32 v72, 0xbfb8aa3b, v72
	v_mul_f32_e32 v73, 0xbfb8aa3b, v73
	v_exp_f32_e32 v72, v72
	v_exp_f32_e32 v73, v73
	v_lshlrev_b32_e32 v74, 16, v101
	v_and_b32_e32 v75, 0xffff0000, v101
	v_add_f32_e32 v72, 1.0, v72
	v_add_f32_e32 v73, 1.0, v73
	v_rcp_f32_e32 v72, v72
	v_rcp_f32_e32 v73, v73
	s_nop 0
	v_pk_fma_f32 v[70:71], v[70:71], v[72:73], v[74:75]
	v_lshlrev_b32_e32 v72, 16, v106
	v_and_b32_e32 v73, 0xffff0000, v106
	v_mul_f32_e32 v72, 0xbfb8aa3b, v72
	v_mul_f32_e32 v73, 0xbfb8aa3b, v73
	v_exp_f32_e32 v72, v72
	v_exp_f32_e32 v73, v73
	v_lshlrev_b32_e32 v74, 16, v102
	v_and_b32_e32 v75, 0xffff0000, v102
	v_add_f32_e32 v72, 1.0, v72
	v_add_f32_e32 v73, 1.0, v73
	v_rcp_f32_e32 v72, v72
	v_rcp_f32_e32 v73, v73
	s_nop 0
	v_pk_fma_f32 v[72:73], v[64:65], v[72:73], v[74:75]
	v_lshlrev_b32_e32 v64, 16, v107
	v_and_b32_e32 v65, 0xffff0000, v107
	v_mul_f32_e32 v64, 0xbfb8aa3b, v64
	v_mul_f32_e32 v65, 0xbfb8aa3b, v65
	v_exp_f32_e32 v64, v64
	v_exp_f32_e32 v65, v65
	v_lshlrev_b32_e32 v74, 16, v103
	v_and_b32_e32 v75, 0xffff0000, v103
	v_add_f32_e32 v64, 1.0, v64
	v_add_f32_e32 v65, 1.0, v65
	v_rcp_f32_e32 v64, v64
	v_rcp_f32_e32 v65, v65
	s_nop 0
	v_pk_fma_f32 v[74:75], v[66:67], v[64:65], v[74:75]
	v_cvt_pk_bf16_f32 v64, v68, v69
	v_cvt_pk_bf16_f32 v65, v70, v71
	v_cvt_pk_bf16_f32 v66, v72, v73
	v_cvt_pk_bf16_f32 v67, v74, v75
	global_store_dwordx4 v[84:85], v[64:67], off offset:256
	s_nop 1
	v_add_u32_e32 v64, 0x80, v186
	v_ashrrev_i32_e32 v65, 31, v64
	v_lshlrev_b32_e32 v66, 9, v64
	v_and_b32_e32 v166, 0x1fe00, v66
	v_lshlrev_b64 v[94:95], 11, v[64:65]
	v_lshl_add_u64 v[66:67], v[188:189], 0, v[166:167]
	v_lshl_add_u64 v[64:65], v[190:191], 0, v[94:95]
	global_load_dwordx4 v[96:99], v[66:67], off
	global_load_dwordx4 v[88:91], v[66:67], off offset:256
	global_load_dwordx4 v[100:103], v[64:65], off
	global_load_dwordx4 v[84:87], v[64:65], off offset:256
	v_add_u32_e32 v64, 0x90, v186
	v_ashrrev_i32_e32 v65, 31, v64
	v_lshlrev_b32_e32 v66, 9, v64
	v_and_b32_e32 v166, 0x1fe00, v66
	v_lshlrev_b64 v[92:93], 11, v[64:65]
	v_lshl_add_u64 v[66:67], v[188:189], 0, v[166:167]
	v_lshl_add_u64 v[64:65], v[190:191], 0, v[92:93]
	global_load_dwordx4 v[76:79], v[66:67], off
	global_load_dwordx4 v[68:71], v[66:67], off offset:256
	global_load_dwordx4 v[72:75], v[64:65], off
	s_nop 0
	global_load_dwordx4 v[64:67], v[64:65], off offset:256
	s_waitcnt vmcnt(0)
	v_lshlrev_b32_e32 v104, 16, v96
	v_and_b32_e32 v96, 0xffff0000, v96
	v_mul_f32_e32 v96, 0xbfb8aa3b, v96
	v_exp_f32_e32 v96, v96
	v_lshlrev_b32_e32 v106, 16, v100
	v_and_b32_e32 v107, 0xffff0000, v100
	v_lshlrev_b32_e32 v100, 16, v101
	v_add_f32_e32 v96, 1.0, v96
	v_rcp_f32_e32 v105, v96
	v_lshlrev_b32_e32 v96, 16, v97
	v_and_b32_e32 v97, 0xffff0000, v97
	v_mul_f32_e32 v96, 0xbfb8aa3b, v96
	v_mul_f32_e32 v97, 0xbfb8aa3b, v97
	v_exp_f32_e32 v96, v96
	v_exp_f32_e32 v97, v97
	v_and_b32_e32 v101, 0xffff0000, v101
	v_mul_f32_e32 v104, 0xbfb8aa3b, v104
	v_add_f32_e32 v96, 1.0, v96
	v_add_f32_e32 v97, 1.0, v97
	v_rcp_f32_e32 v96, v96
	v_rcp_f32_e32 v97, v97
	v_exp_f32_e32 v104, v104
	v_lshl_add_u64 v[94:95], v[184:185], 0, v[94:95]
	v_pk_fma_f32 v[62:63], v[62:63], v[96:97], v[100:101]
	v_lshlrev_b32_e32 v96, 16, v98
	v_and_b32_e32 v97, 0xffff0000, v98
	v_mul_f32_e32 v96, 0xbfb8aa3b, v96
	v_mul_f32_e32 v97, 0xbfb8aa3b, v97
	v_exp_f32_e32 v96, v96
	v_exp_f32_e32 v97, v97
	v_lshlrev_b32_e32 v100, 16, v102
	v_and_b32_e32 v101, 0xffff0000, v102
	v_add_f32_e32 v96, 1.0, v96
	v_add_f32_e32 v97, 1.0, v97
	v_rcp_f32_e32 v96, v96
	v_rcp_f32_e32 v97, v97
	v_add_f32_e32 v104, 1.0, v104
	v_rcp_f32_e32 v104, v104
	v_lshlrev_b32_e32 v98, 16, v103
	v_pk_fma_f32 v[96:97], v[56:57], v[96:97], v[100:101]
	v_lshlrev_b32_e32 v56, 16, v99
	v_and_b32_e32 v57, 0xffff0000, v99
	v_mul_f32_e32 v56, 0xbfb8aa3b, v56
	v_mul_f32_e32 v57, 0xbfb8aa3b, v57
	v_exp_f32_e32 v56, v56
	v_exp_f32_e32 v57, v57
	v_and_b32_e32 v99, 0xffff0000, v103
	v_pk_fma_f32 v[60:61], v[60:61], v[104:105], v[106:107]
	v_add_f32_e32 v56, 1.0, v56
	v_add_f32_e32 v57, 1.0, v57
	v_rcp_f32_e32 v56, v56
	v_rcp_f32_e32 v57, v57
	s_nop 0
	v_pk_fma_f32 v[98:99], v[58:59], v[56:57], v[98:99]
	v_cvt_pk_bf16_f32 v56, v60, v61
	v_cvt_pk_bf16_f32 v57, v62, v63
	v_cvt_pk_bf16_f32 v58, v96, v97
	v_cvt_pk_bf16_f32 v59, v98, v99
	global_store_dwordx4 v[94:95], v[56:59], off
	s_nop 1
	v_lshlrev_b32_e32 v56, 16, v88
	v_and_b32_e32 v57, 0xffff0000, v88
	v_mul_f32_e32 v56, 0xbfb8aa3b, v56
	v_mul_f32_e32 v57, 0xbfb8aa3b, v57
	v_exp_f32_e32 v56, v56
	v_exp_f32_e32 v57, v57
	v_lshlrev_b32_e32 v58, 16, v84
	v_and_b32_e32 v59, 0xffff0000, v84
	v_add_f32_e32 v56, 1.0, v56
	v_add_f32_e32 v57, 1.0, v57
	v_rcp_f32_e32 v56, v56
	v_rcp_f32_e32 v57, v57
	s_nop 0
	v_pk_fma_f32 v[52:53], v[52:53], v[56:57], v[58:59]
	v_lshlrev_b32_e32 v56, 16, v89
	v_and_b32_e32 v57, 0xffff0000, v89
	v_mul_f32_e32 v56, 0xbfb8aa3b, v56
	v_mul_f32_e32 v57, 0xbfb8aa3b, v57
	v_exp_f32_e32 v56, v56
	v_exp_f32_e32 v57, v57
	v_lshlrev_b32_e32 v58, 16, v85
	v_and_b32_e32 v59, 0xffff0000, v85
	v_add_f32_e32 v56, 1.0, v56
	v_add_f32_e32 v57, 1.0, v57
	v_rcp_f32_e32 v56, v56
	v_rcp_f32_e32 v57, v57
	s_nop 0
	v_pk_fma_f32 v[54:55], v[54:55], v[56:57], v[58:59]
	v_lshlrev_b32_e32 v56, 16, v90
	v_and_b32_e32 v57, 0xffff0000, v90
	v_mul_f32_e32 v56, 0xbfb8aa3b, v56
	v_mul_f32_e32 v57, 0xbfb8aa3b, v57
	v_exp_f32_e32 v56, v56
	v_exp_f32_e32 v57, v57
	v_lshlrev_b32_e32 v58, 16, v86
	v_and_b32_e32 v59, 0xffff0000, v86
	v_add_f32_e32 v56, 1.0, v56
	v_add_f32_e32 v57, 1.0, v57
	v_rcp_f32_e32 v56, v56
	v_rcp_f32_e32 v57, v57
	s_nop 0
	v_pk_fma_f32 v[56:57], v[48:49], v[56:57], v[58:59]
	v_lshlrev_b32_e32 v48, 16, v91
	v_and_b32_e32 v49, 0xffff0000, v91
	v_mul_f32_e32 v48, 0xbfb8aa3b, v48
	v_mul_f32_e32 v49, 0xbfb8aa3b, v49
	v_exp_f32_e32 v48, v48
	v_exp_f32_e32 v49, v49
	v_lshlrev_b32_e32 v58, 16, v87
	v_and_b32_e32 v59, 0xffff0000, v87
	v_add_f32_e32 v48, 1.0, v48
	v_add_f32_e32 v49, 1.0, v49
	v_rcp_f32_e32 v48, v48
	v_rcp_f32_e32 v49, v49
	s_nop 0
	v_pk_fma_f32 v[58:59], v[50:51], v[48:49], v[58:59]
	v_cvt_pk_bf16_f32 v48, v52, v53
	v_cvt_pk_bf16_f32 v49, v54, v55
	v_cvt_pk_bf16_f32 v50, v56, v57
	v_cvt_pk_bf16_f32 v51, v58, v59
	global_store_dwordx4 v[94:95], v[48:51], off offset:256
	v_lshlrev_b32_e32 v52, 16, v72
	v_and_b32_e32 v53, 0xffff0000, v72
	v_lshlrev_b32_e32 v50, 16, v76
	v_and_b32_e32 v51, 0xffff0000, v76
	v_mul_f32_e32 v50, 0xbfb8aa3b, v50
	v_mul_f32_e32 v51, 0xbfb8aa3b, v51
	v_exp_f32_e32 v50, v50
	v_exp_f32_e32 v51, v51
	v_lshl_add_u64 v[48:49], v[184:185], 0, v[92:93]
	v_add_f32_e32 v50, 1.0, v50
	v_add_f32_e32 v51, 1.0, v51
	v_rcp_f32_e32 v50, v50
	v_rcp_f32_e32 v51, v51
	s_nop 0
	v_pk_fma_f32 v[44:45], v[44:45], v[50:51], v[52:53]
	v_lshlrev_b32_e32 v50, 16, v77
	v_and_b32_e32 v51, 0xffff0000, v77
	v_mul_f32_e32 v50, 0xbfb8aa3b, v50
	v_mul_f32_e32 v51, 0xbfb8aa3b, v51
	v_exp_f32_e32 v50, v50
	v_exp_f32_e32 v51, v51
	v_lshlrev_b32_e32 v52, 16, v73
	v_and_b32_e32 v53, 0xffff0000, v73
	v_add_f32_e32 v50, 1.0, v50
	v_add_f32_e32 v51, 1.0, v51
	v_rcp_f32_e32 v50, v50
	v_rcp_f32_e32 v51, v51
	s_nop 0
	v_pk_fma_f32 v[46:47], v[46:47], v[50:51], v[52:53]
	v_lshlrev_b32_e32 v50, 16, v78
	v_and_b32_e32 v51, 0xffff0000, v78
	v_mul_f32_e32 v50, 0xbfb8aa3b, v50
	v_mul_f32_e32 v51, 0xbfb8aa3b, v51
	v_exp_f32_e32 v50, v50
	v_exp_f32_e32 v51, v51
	v_lshlrev_b32_e32 v52, 16, v74
	v_and_b32_e32 v53, 0xffff0000, v74
	v_add_f32_e32 v50, 1.0, v50
	v_add_f32_e32 v51, 1.0, v51
	v_rcp_f32_e32 v50, v50
	v_rcp_f32_e32 v51, v51
	s_nop 0
	v_pk_fma_f32 v[50:51], v[40:41], v[50:51], v[52:53]
	v_lshlrev_b32_e32 v40, 16, v79
	v_and_b32_e32 v41, 0xffff0000, v79
	v_mul_f32_e32 v40, 0xbfb8aa3b, v40
	v_mul_f32_e32 v41, 0xbfb8aa3b, v41
	v_exp_f32_e32 v40, v40
	v_exp_f32_e32 v41, v41
	v_lshlrev_b32_e32 v52, 16, v75
	v_and_b32_e32 v53, 0xffff0000, v75
	v_add_f32_e32 v40, 1.0, v40
	v_add_f32_e32 v41, 1.0, v41
	v_rcp_f32_e32 v40, v40
	v_rcp_f32_e32 v41, v41
	s_nop 0
	v_pk_fma_f32 v[52:53], v[42:43], v[40:41], v[52:53]
	v_cvt_pk_bf16_f32 v40, v44, v45
	v_cvt_pk_bf16_f32 v41, v46, v47
	v_cvt_pk_bf16_f32 v42, v50, v51
	v_cvt_pk_bf16_f32 v43, v52, v53
	global_store_dwordx4 v[48:49], v[40:43], off
	s_nop 1
	v_lshlrev_b32_e32 v40, 16, v68
	v_and_b32_e32 v41, 0xffff0000, v68
	v_mul_f32_e32 v40, 0xbfb8aa3b, v40
	v_mul_f32_e32 v41, 0xbfb8aa3b, v41
	v_exp_f32_e32 v40, v40
	v_exp_f32_e32 v41, v41
	v_lshlrev_b32_e32 v42, 16, v64
	v_and_b32_e32 v43, 0xffff0000, v64
	v_add_f32_e32 v40, 1.0, v40
	v_add_f32_e32 v41, 1.0, v41
	v_rcp_f32_e32 v40, v40
	v_rcp_f32_e32 v41, v41
	s_nop 0
	v_pk_fma_f32 v[36:37], v[36:37], v[40:41], v[42:43]
	v_lshlrev_b32_e32 v40, 16, v69
	v_and_b32_e32 v41, 0xffff0000, v69
	v_mul_f32_e32 v40, 0xbfb8aa3b, v40
	v_mul_f32_e32 v41, 0xbfb8aa3b, v41
	v_exp_f32_e32 v40, v40
	v_exp_f32_e32 v41, v41
	v_lshlrev_b32_e32 v42, 16, v65
	v_and_b32_e32 v43, 0xffff0000, v65
	v_add_f32_e32 v40, 1.0, v40
	v_add_f32_e32 v41, 1.0, v41
	v_rcp_f32_e32 v40, v40
	v_rcp_f32_e32 v41, v41
	s_nop 0
	v_pk_fma_f32 v[38:39], v[38:39], v[40:41], v[42:43]
	v_lshlrev_b32_e32 v40, 16, v70
	v_and_b32_e32 v41, 0xffff0000, v70
	v_mul_f32_e32 v40, 0xbfb8aa3b, v40
	v_mul_f32_e32 v41, 0xbfb8aa3b, v41
	v_exp_f32_e32 v40, v40
	v_exp_f32_e32 v41, v41
	v_lshlrev_b32_e32 v42, 16, v66
	v_and_b32_e32 v43, 0xffff0000, v66
	v_add_f32_e32 v40, 1.0, v40
	v_add_f32_e32 v41, 1.0, v41
	v_rcp_f32_e32 v40, v40
	v_rcp_f32_e32 v41, v41
	s_nop 0
	v_pk_fma_f32 v[40:41], v[32:33], v[40:41], v[42:43]
	v_lshlrev_b32_e32 v32, 16, v71
	v_and_b32_e32 v33, 0xffff0000, v71
	v_mul_f32_e32 v32, 0xbfb8aa3b, v32
	v_mul_f32_e32 v33, 0xbfb8aa3b, v33
	v_exp_f32_e32 v32, v32
	v_exp_f32_e32 v33, v33
	v_lshlrev_b32_e32 v42, 16, v67
	v_and_b32_e32 v43, 0xffff0000, v67
	v_add_f32_e32 v32, 1.0, v32
	v_add_f32_e32 v33, 1.0, v33
	v_rcp_f32_e32 v32, v32
	v_rcp_f32_e32 v33, v33
	s_nop 0
	v_pk_fma_f32 v[42:43], v[34:35], v[32:33], v[42:43]
	v_cvt_pk_bf16_f32 v32, v36, v37
	v_cvt_pk_bf16_f32 v33, v38, v39
	v_cvt_pk_bf16_f32 v34, v40, v41
	v_cvt_pk_bf16_f32 v35, v42, v43
	global_store_dwordx4 v[48:49], v[32:35], off offset:256
	s_nop 1
	v_add_u32_e32 v32, 0xa0, v186
	v_ashrrev_i32_e32 v33, 31, v32
	v_lshlrev_b32_e32 v34, 9, v32
	v_and_b32_e32 v166, 0x1fe00, v34
	v_lshlrev_b64 v[58:59], 11, v[32:33]
	v_lshl_add_u64 v[34:35], v[188:189], 0, v[166:167]
	v_lshl_add_u64 v[32:33], v[190:191], 0, v[58:59]
	global_load_dwordx4 v[60:63], v[34:35], off
	global_load_dwordx4 v[52:55], v[34:35], off offset:256
	global_load_dwordx4 v[64:67], v[32:33], off
	global_load_dwordx4 v[48:51], v[32:33], off offset:256
	v_add_u32_e32 v32, 0xb0, v186
	v_ashrrev_i32_e32 v33, 31, v32
	v_lshlrev_b32_e32 v34, 9, v32
	v_and_b32_e32 v166, 0x1fe00, v34
	v_lshlrev_b64 v[56:57], 11, v[32:33]
	v_lshl_add_u64 v[34:35], v[188:189], 0, v[166:167]
	v_lshl_add_u64 v[32:33], v[190:191], 0, v[56:57]
	global_load_dwordx4 v[44:47], v[34:35], off
	global_load_dwordx4 v[36:39], v[34:35], off offset:256
	global_load_dwordx4 v[40:43], v[32:33], off
	s_nop 0
	global_load_dwordx4 v[32:35], v[32:33], off offset:256
	s_waitcnt vmcnt(0)
	v_lshlrev_b32_e32 v68, 16, v60
	v_and_b32_e32 v60, 0xffff0000, v60
	v_mul_f32_e32 v60, 0xbfb8aa3b, v60
	v_exp_f32_e32 v60, v60
	v_lshlrev_b32_e32 v70, 16, v64
	v_and_b32_e32 v71, 0xffff0000, v64
	v_lshlrev_b32_e32 v64, 16, v65
	v_add_f32_e32 v60, 1.0, v60
	v_rcp_f32_e32 v69, v60
	v_lshlrev_b32_e32 v60, 16, v61
	v_and_b32_e32 v61, 0xffff0000, v61
	v_mul_f32_e32 v60, 0xbfb8aa3b, v60
	v_mul_f32_e32 v61, 0xbfb8aa3b, v61
	v_exp_f32_e32 v60, v60
	v_exp_f32_e32 v61, v61
	v_and_b32_e32 v65, 0xffff0000, v65
	v_mul_f32_e32 v68, 0xbfb8aa3b, v68
	v_add_f32_e32 v60, 1.0, v60
	v_add_f32_e32 v61, 1.0, v61
	v_rcp_f32_e32 v60, v60
	v_rcp_f32_e32 v61, v61
	v_exp_f32_e32 v68, v68
	v_lshl_add_u64 v[58:59], v[184:185], 0, v[58:59]
	v_pk_fma_f32 v[30:31], v[30:31], v[60:61], v[64:65]
	v_lshlrev_b32_e32 v60, 16, v62
	v_and_b32_e32 v61, 0xffff0000, v62
	v_mul_f32_e32 v60, 0xbfb8aa3b, v60
	v_mul_f32_e32 v61, 0xbfb8aa3b, v61
	v_exp_f32_e32 v60, v60
	v_exp_f32_e32 v61, v61
	v_lshlrev_b32_e32 v64, 16, v66
	v_and_b32_e32 v65, 0xffff0000, v66
	v_add_f32_e32 v60, 1.0, v60
	v_add_f32_e32 v61, 1.0, v61
	v_rcp_f32_e32 v60, v60
	v_rcp_f32_e32 v61, v61
	v_add_f32_e32 v68, 1.0, v68
	v_rcp_f32_e32 v68, v68
	v_lshlrev_b32_e32 v62, 16, v67
	v_pk_fma_f32 v[60:61], v[24:25], v[60:61], v[64:65]
	v_lshlrev_b32_e32 v24, 16, v63
	v_and_b32_e32 v25, 0xffff0000, v63
	v_mul_f32_e32 v24, 0xbfb8aa3b, v24
	v_mul_f32_e32 v25, 0xbfb8aa3b, v25
	v_exp_f32_e32 v24, v24
	v_exp_f32_e32 v25, v25
	v_and_b32_e32 v63, 0xffff0000, v67
	v_pk_fma_f32 v[28:29], v[28:29], v[68:69], v[70:71]
	v_add_f32_e32 v24, 1.0, v24
	v_add_f32_e32 v25, 1.0, v25
	v_rcp_f32_e32 v24, v24
	v_rcp_f32_e32 v25, v25
	s_nop 0
	v_pk_fma_f32 v[62:63], v[26:27], v[24:25], v[62:63]
	v_cvt_pk_bf16_f32 v24, v28, v29
	v_cvt_pk_bf16_f32 v25, v30, v31
	v_cvt_pk_bf16_f32 v26, v60, v61
	v_cvt_pk_bf16_f32 v27, v62, v63
	global_store_dwordx4 v[58:59], v[24:27], off
	s_nop 1
	v_lshlrev_b32_e32 v24, 16, v52
	v_and_b32_e32 v25, 0xffff0000, v52
	v_mul_f32_e32 v24, 0xbfb8aa3b, v24
	v_mul_f32_e32 v25, 0xbfb8aa3b, v25
	v_exp_f32_e32 v24, v24
	v_exp_f32_e32 v25, v25
	v_lshlrev_b32_e32 v26, 16, v48
	v_and_b32_e32 v27, 0xffff0000, v48
	v_add_f32_e32 v24, 1.0, v24
	v_add_f32_e32 v25, 1.0, v25
	v_rcp_f32_e32 v24, v24
	v_rcp_f32_e32 v25, v25
	s_nop 0
	v_pk_fma_f32 v[20:21], v[20:21], v[24:25], v[26:27]
	v_lshlrev_b32_e32 v24, 16, v53
	v_and_b32_e32 v25, 0xffff0000, v53
	v_mul_f32_e32 v24, 0xbfb8aa3b, v24
	v_mul_f32_e32 v25, 0xbfb8aa3b, v25
	v_exp_f32_e32 v24, v24
	v_exp_f32_e32 v25, v25
	v_lshlrev_b32_e32 v26, 16, v49
	v_and_b32_e32 v27, 0xffff0000, v49
	v_add_f32_e32 v24, 1.0, v24
	v_add_f32_e32 v25, 1.0, v25
	v_rcp_f32_e32 v24, v24
	v_rcp_f32_e32 v25, v25
	s_nop 0
	v_pk_fma_f32 v[22:23], v[22:23], v[24:25], v[26:27]
	v_lshlrev_b32_e32 v24, 16, v54
	v_and_b32_e32 v25, 0xffff0000, v54
	v_mul_f32_e32 v24, 0xbfb8aa3b, v24
	v_mul_f32_e32 v25, 0xbfb8aa3b, v25
	v_exp_f32_e32 v24, v24
	v_exp_f32_e32 v25, v25
	v_lshlrev_b32_e32 v26, 16, v50
	v_and_b32_e32 v27, 0xffff0000, v50
	v_add_f32_e32 v24, 1.0, v24
	v_add_f32_e32 v25, 1.0, v25
	v_rcp_f32_e32 v24, v24
	v_rcp_f32_e32 v25, v25
	s_nop 0
	v_pk_fma_f32 v[24:25], v[16:17], v[24:25], v[26:27]
	v_lshlrev_b32_e32 v16, 16, v55
	v_and_b32_e32 v17, 0xffff0000, v55
	v_mul_f32_e32 v16, 0xbfb8aa3b, v16
	v_mul_f32_e32 v17, 0xbfb8aa3b, v17
	v_exp_f32_e32 v16, v16
	v_exp_f32_e32 v17, v17
	v_lshlrev_b32_e32 v26, 16, v51
	v_and_b32_e32 v27, 0xffff0000, v51
	v_add_f32_e32 v16, 1.0, v16
	v_add_f32_e32 v17, 1.0, v17
	v_rcp_f32_e32 v16, v16
	v_rcp_f32_e32 v17, v17
	s_nop 0
	v_pk_fma_f32 v[26:27], v[18:19], v[16:17], v[26:27]
	v_cvt_pk_bf16_f32 v16, v20, v21
	v_cvt_pk_bf16_f32 v17, v22, v23
	v_cvt_pk_bf16_f32 v18, v24, v25
	v_cvt_pk_bf16_f32 v19, v26, v27
	global_store_dwordx4 v[58:59], v[16:19], off offset:256
	v_lshlrev_b32_e32 v20, 16, v40
	v_and_b32_e32 v21, 0xffff0000, v40
	v_lshlrev_b32_e32 v18, 16, v44
	v_and_b32_e32 v19, 0xffff0000, v44
	v_mul_f32_e32 v18, 0xbfb8aa3b, v18
	v_mul_f32_e32 v19, 0xbfb8aa3b, v19
	v_exp_f32_e32 v18, v18
	v_exp_f32_e32 v19, v19
	v_lshl_add_u64 v[16:17], v[184:185], 0, v[56:57]
	v_add_f32_e32 v18, 1.0, v18
	v_add_f32_e32 v19, 1.0, v19
	v_rcp_f32_e32 v18, v18
	v_rcp_f32_e32 v19, v19
	s_nop 0
	v_pk_fma_f32 v[12:13], v[12:13], v[18:19], v[20:21]
	v_lshlrev_b32_e32 v18, 16, v45
	v_and_b32_e32 v19, 0xffff0000, v45
	v_mul_f32_e32 v18, 0xbfb8aa3b, v18
	v_mul_f32_e32 v19, 0xbfb8aa3b, v19
	v_exp_f32_e32 v18, v18
	v_exp_f32_e32 v19, v19
	v_lshlrev_b32_e32 v20, 16, v41
	v_and_b32_e32 v21, 0xffff0000, v41
	v_add_f32_e32 v18, 1.0, v18
	v_add_f32_e32 v19, 1.0, v19
	v_rcp_f32_e32 v18, v18
	v_rcp_f32_e32 v19, v19
	s_nop 0
	v_pk_fma_f32 v[14:15], v[14:15], v[18:19], v[20:21]
	v_lshlrev_b32_e32 v18, 16, v46
	v_and_b32_e32 v19, 0xffff0000, v46
	v_mul_f32_e32 v18, 0xbfb8aa3b, v18
	v_mul_f32_e32 v19, 0xbfb8aa3b, v19
	v_exp_f32_e32 v18, v18
	v_exp_f32_e32 v19, v19
	v_lshlrev_b32_e32 v20, 16, v42
	v_and_b32_e32 v21, 0xffff0000, v42
	v_add_f32_e32 v18, 1.0, v18
	v_add_f32_e32 v19, 1.0, v19
	v_rcp_f32_e32 v18, v18
	v_rcp_f32_e32 v19, v19
	s_nop 0
	v_pk_fma_f32 v[18:19], v[8:9], v[18:19], v[20:21]
	v_lshlrev_b32_e32 v8, 16, v47
	v_and_b32_e32 v9, 0xffff0000, v47
	v_mul_f32_e32 v8, 0xbfb8aa3b, v8
	v_mul_f32_e32 v9, 0xbfb8aa3b, v9
	v_exp_f32_e32 v8, v8
	v_exp_f32_e32 v9, v9
	v_lshlrev_b32_e32 v20, 16, v43
	v_and_b32_e32 v21, 0xffff0000, v43
	v_add_f32_e32 v8, 1.0, v8
	v_add_f32_e32 v9, 1.0, v9
	v_rcp_f32_e32 v8, v8
	v_rcp_f32_e32 v9, v9
	s_nop 0
	v_pk_fma_f32 v[20:21], v[10:11], v[8:9], v[20:21]
	v_cvt_pk_bf16_f32 v8, v12, v13
	v_cvt_pk_bf16_f32 v9, v14, v15
	v_cvt_pk_bf16_f32 v10, v18, v19
	v_cvt_pk_bf16_f32 v11, v20, v21
	global_store_dwordx4 v[16:17], v[8:11], off
	s_nop 1
	v_lshlrev_b32_e32 v8, 16, v36
	v_and_b32_e32 v9, 0xffff0000, v36
	v_mul_f32_e32 v8, 0xbfb8aa3b, v8
	v_mul_f32_e32 v9, 0xbfb8aa3b, v9
	v_exp_f32_e32 v8, v8
	v_exp_f32_e32 v9, v9
	v_lshlrev_b32_e32 v10, 16, v32
	v_and_b32_e32 v11, 0xffff0000, v32
	v_add_f32_e32 v8, 1.0, v8
	v_add_f32_e32 v9, 1.0, v9
	v_rcp_f32_e32 v8, v8
	v_rcp_f32_e32 v9, v9
	s_nop 0
	v_pk_fma_f32 v[4:5], v[4:5], v[8:9], v[10:11]
	v_lshlrev_b32_e32 v8, 16, v37
	v_and_b32_e32 v9, 0xffff0000, v37
	v_mul_f32_e32 v8, 0xbfb8aa3b, v8
	v_mul_f32_e32 v9, 0xbfb8aa3b, v9
	v_exp_f32_e32 v8, v8
	v_exp_f32_e32 v9, v9
	v_lshlrev_b32_e32 v10, 16, v33
	v_and_b32_e32 v11, 0xffff0000, v33
	v_add_f32_e32 v8, 1.0, v8
	v_add_f32_e32 v9, 1.0, v9
	v_rcp_f32_e32 v8, v8
	v_rcp_f32_e32 v9, v9
	s_nop 0
	v_pk_fma_f32 v[6:7], v[6:7], v[8:9], v[10:11]
	v_lshlrev_b32_e32 v8, 16, v38
	v_and_b32_e32 v9, 0xffff0000, v38
	v_mul_f32_e32 v8, 0xbfb8aa3b, v8
	v_mul_f32_e32 v9, 0xbfb8aa3b, v9
	v_exp_f32_e32 v8, v8
	v_exp_f32_e32 v9, v9
	v_lshlrev_b32_e32 v10, 16, v34
	v_and_b32_e32 v11, 0xffff0000, v34
	v_add_f32_e32 v8, 1.0, v8
	v_add_f32_e32 v9, 1.0, v9
	v_rcp_f32_e32 v8, v8
	v_rcp_f32_e32 v9, v9
	s_nop 0
	v_pk_fma_f32 v[8:9], v[0:1], v[8:9], v[10:11]
	v_lshlrev_b32_e32 v0, 16, v39
	v_and_b32_e32 v1, 0xffff0000, v39
	v_mul_f32_e32 v0, 0xbfb8aa3b, v0
	v_mul_f32_e32 v1, 0xbfb8aa3b, v1
	v_exp_f32_e32 v0, v0
	v_exp_f32_e32 v1, v1
	v_lshlrev_b32_e32 v10, 16, v35
	v_and_b32_e32 v11, 0xffff0000, v35
	v_add_f32_e32 v0, 1.0, v0
	v_add_f32_e32 v1, 1.0, v1
	v_rcp_f32_e32 v0, v0
	v_rcp_f32_e32 v1, v1
	s_nop 0
	v_pk_fma_f32 v[10:11], v[2:3], v[0:1], v[10:11]
	v_cvt_pk_bf16_f32 v0, v4, v5
	v_cvt_pk_bf16_f32 v1, v6, v7
	v_cvt_pk_bf16_f32 v2, v8, v9
	v_cvt_pk_bf16_f32 v3, v10, v11
	global_store_dwordx4 v[16:17], v[0:3], off offset:256

.LBB0_1803:
	s_ashr_i32 s12, s22, 3
	s_add_i32 s12, s40, s12
	s_ashr_i32 s13, s12, 31
	s_lshr_b32 s13, s13, 28
	s_add_i32 s13, s12, s13
	s_ashr_i32 s22, s13, 4
	s_lshl_b32 s22, s22, 2
	s_sub_i32 s23, 64, s22
	s_min_i32 s23, s23, 4
	s_abs_i32 s40, s23
	v_cvt_f32_u32_e32 v216, s40
	s_sub_i32 s44, 0, s40
	s_and_b32 s13, s13, -16
	s_sub_i32 s12, s12, s13
	v_rcp_iflag_f32_e32 v216, v216
	s_abs_i32 s13, s12
	s_xor_b32 s41, s12, s23
	s_ashr_i32 s41, s41, 31
	v_mul_f32_e32 v216, 0x4f7ffffe, v216
	v_cvt_u32_f32_e32 v216, v216
	s_nop 0
	v_readfirstlane_b32 s45, v216
	s_mul_i32 s44, s44, s45
	s_mul_hi_u32 s44, s45, s44
	s_add_i32 s45, s45, s44
	s_mul_hi_u32 s44, s13, s45
	s_mul_i32 s45, s44, s40
	s_sub_i32 s13, s13, s45
	s_add_i32 s46, s44, 1
	s_sub_i32 s45, s13, s40
	s_cmp_ge_u32 s13, s40
	s_cselect_b32 s44, s46, s44
	s_cselect_b32 s13, s45, s13
	s_add_i32 s45, s44, 1
	s_cmp_ge_u32 s13, s40
	s_cselect_b32 s13, s45, s44
	s_xor_b32 s13, s13, s41
	s_sub_i32 s40, s13, s41
	s_mul_i32 s13, s40, s23
	s_sub_i32 s12, s12, s13
	s_add_i32 s41, s22, s12
.LBB0_1804:
	v_cndmask_b32_e64 v216, 0, 1, s[10:11]
	v_cmp_ne_u32_e64 s[12:13], 1, v216
	s_andn2_b64 vcc, exec, s[10:11]
	s_mov_b64 s[10:11], s[20:21]
	s_cbranch_vccnz .LBB0_1806
	s_ashr_i32 s10, s41, 31
	s_mul_hi_u32 s11, s14, s41
	s_mul_i32 s10, s14, s10
	s_add_i32 s10, s11, s10
	s_mul_i32 s11, s15, s41
	s_add_i32 s11, s10, s11
	s_mul_i32 s10, s14, s41
	s_add_u32 s10, s24, s10
	s_addc_u32 s11, s5, s11

.LBB0_1808:
	s_andn2_b64 vcc, exec, s[16:17]
	s_cbranch_vccnz .LBB0_1797
	s_add_u32 s44, s18, 0x100
	s_addc_u32 s45, s19, 0
	s_add_u32 s18, s20, 0x80
	s_addc_u32 s19, s21, 0
	s_mov_b32 s20, 0
